# GEMM K-loops: also dropped the redundant hipcc s_waitcnt lgkmcnt(0) at the head of each MFMA section (after the asm drain + barrier)
# baseline (speedup 1.0000x reference)
.LBB0_163:
	ds_read_b128 v[148:151], v177
	ds_read_b128 v[152:155], v177 offset:1024
	ds_read_b128 v[156:159], v177 offset:2048
	ds_read_b128 v[182:185], v177 offset:3072
	ds_read_b128 v[186:189], v178
	ds_read_b128 v[190:193], v178 offset:1024
	ds_read_b128 v[194:197], v178 offset:2048
	ds_read_b128 v[198:201], v178 offset:3072
	s_add_u32 s36, s34, 0xfff80080
	s_addc_u32 s37, s35, -1
	s_cmp_eq_u32 s64, 28
	s_cselect_b32 s39, s2, s37
	s_cselect_b32 s38, s3, s36
	s_cselect_b32 s37, s7, s63
	s_cselect_b32 s36, s23, s25
	v_lshl_add_u64 v[160:161], s[34:35], 0, v[142:143]
	s_add_i32 m0, s31, 0xc000
	ds_read_b128 v[202:205], v180
	ds_read_b128 v[210:213], v180 offset:1024
	ds_read_b128 v[214:217], v180 offset:2048
	ds_read_b128 v[218:221], v180 offset:3072
	ds_read_b128 v[222:225], v180 offset:4096
	ds_read_b128 v[226:229], v180 offset:5120
	ds_read_b128 v[230:233], v180 offset:6144
	ds_read_b128 v[234:237], v180 offset:7168
	global_load_lds_dwordx4 v[160:161], off
	v_lshl_add_u64 v[160:161], s[34:35], 0, v[144:145]
	s_add_i32 m0, s31, 0xe000
	s_nop 0
	global_load_lds_dwordx4 v[160:161], off
	s_waitcnt vmcnt(8)
	s_waitcnt lgkmcnt(0)
	s_barrier
	s_setprio 1
	v_mfma_f32_16x16x32_bf16 v[124:127], v[148:151], v[202:205], v[124:127]
	v_mfma_f32_16x16x32_bf16 v[120:123], v[156:159], v[202:205], v[120:123]
	v_mfma_f32_16x16x32_bf16 v[108:111], v[148:151], v[214:217], v[108:111]
	v_mfma_f32_16x16x32_bf16 v[104:107], v[156:159], v[214:217], v[104:107]
	v_mfma_f32_16x16x32_bf16 v[92:95], v[148:151], v[222:225], v[92:95]
	v_mfma_f32_16x16x32_bf16 v[88:91], v[156:159], v[222:225], v[88:91]
	v_mfma_f32_16x16x32_bf16 v[76:79], v[148:151], v[230:233], v[76:79]
	v_mfma_f32_16x16x32_bf16 v[72:75], v[156:159], v[230:233], v[72:75]
	v_mfma_f32_16x16x32_bf16 v[124:127], v[152:155], v[210:213], v[124:127]
	v_mfma_f32_16x16x32_bf16 v[120:123], v[182:185], v[210:213], v[120:123]
	v_mfma_f32_16x16x32_bf16 v[108:111], v[152:155], v[218:221], v[108:111]
	v_mfma_f32_16x16x32_bf16 v[104:107], v[182:185], v[218:221], v[104:107]
	v_mfma_f32_16x16x32_bf16 v[92:95], v[152:155], v[226:229], v[92:95]
	v_mfma_f32_16x16x32_bf16 v[88:91], v[182:185], v[226:229], v[88:91]
	v_mfma_f32_16x16x32_bf16 v[76:79], v[152:155], v[234:237], v[76:79]
	v_mfma_f32_16x16x32_bf16 v[72:75], v[182:185], v[234:237], v[72:75]
	v_mfma_f32_16x16x32_bf16 v[116:119], v[186:189], v[202:205], v[116:119]
	v_mfma_f32_16x16x32_bf16 v[112:115], v[194:197], v[202:205], v[112:115]
	v_mfma_f32_16x16x32_bf16 v[100:103], v[186:189], v[214:217], v[100:103]
	v_mfma_f32_16x16x32_bf16 v[96:99], v[194:197], v[214:217], v[96:99]
	v_mfma_f32_16x16x32_bf16 v[84:87], v[186:189], v[222:225], v[84:87]
	v_mfma_f32_16x16x32_bf16 v[80:83], v[194:197], v[222:225], v[80:83]
	v_mfma_f32_16x16x32_bf16 v[68:71], v[186:189], v[230:233], v[68:71]
	v_mfma_f32_16x16x32_bf16 v[64:67], v[194:197], v[230:233], v[64:67]
	v_mfma_f32_16x16x32_bf16 v[116:119], v[190:193], v[210:213], v[116:119]
	v_mfma_f32_16x16x32_bf16 v[112:115], v[198:201], v[210:213], v[112:115]
	v_mfma_f32_16x16x32_bf16 v[100:103], v[190:193], v[218:221], v[100:103]
	v_mfma_f32_16x16x32_bf16 v[96:99], v[198:201], v[218:221], v[96:99]
	v_mfma_f32_16x16x32_bf16 v[84:87], v[190:193], v[226:229], v[84:87]
	v_mfma_f32_16x16x32_bf16 v[80:83], v[198:201], v[226:229], v[80:83]
	v_mfma_f32_16x16x32_bf16 v[68:71], v[190:193], v[234:237], v[68:71]
	v_mfma_f32_16x16x32_bf16 v[64:67], v[198:201], v[234:237], v[64:67]
	s_setprio 0
	s_barrier
	s_add_i32 s65, s50, s41
	v_lshl_add_u64 v[160:161], s[36:37], 0, v[132:133]
	s_mov_b32 m0, s65
	ds_read_b128 v[202:205], v180 offset:16384
	ds_read_b128 v[210:213], v180 offset:17408
	ds_read_b128 v[214:217], v180 offset:18432
	ds_read_b128 v[218:221], v180 offset:19456
	ds_read_b128 v[222:225], v180 offset:20480
	ds_read_b128 v[226:229], v180 offset:21504
	ds_read_b128 v[230:233], v180 offset:22528
	ds_read_b128 v[234:237], v180 offset:23552
	global_load_lds_dwordx4 v[160:161], off
	s_add_i32 m0, s65, 0x2000
	s_add_u32 s66, s36, 0x80000
	v_lshl_add_u64 v[206:207], s[36:37], 0, v[136:137]
	s_addc_u32 s67, s37, 0
	s_add_i32 s65, s51, s41
	global_load_lds_dwordx4 v[206:207], off
	v_lshl_add_u64 v[238:239], s[66:67], 0, v[132:133]
	s_mov_b32 m0, s65
	v_lshl_add_u64 v[240:241], s[38:39], 0, v[134:135]
	global_load_lds_dwordx4 v[238:239], off
	v_lshl_add_u64 v[238:239], s[66:67], 0, v[136:137]
	s_add_i32 m0, s65, 0x2000
	s_nop 0
	global_load_lds_dwordx4 v[238:239], off
	v_lshl_add_u64 v[238:239], s[38:39], 0, v[130:131]
	s_mov_b32 m0, s31
	s_nop 0
	global_load_lds_dwordx4 v[238:239], off
	s_mov_b32 m0, s42
	s_nop 0
	global_load_lds_dwordx4 v[240:241], off
	s_waitcnt vmcnt(8)
	s_waitcnt lgkmcnt(0)
	s_barrier
	s_setprio 1
	v_mfma_f32_16x16x32_bf16 v[60:63], v[148:151], v[202:205], v[60:63]
	v_mfma_f32_16x16x32_bf16 v[56:59], v[156:159], v[202:205], v[56:59]
	v_mfma_f32_16x16x32_bf16 v[44:47], v[148:151], v[214:217], v[44:47]
	v_mfma_f32_16x16x32_bf16 v[40:43], v[156:159], v[214:217], v[40:43]
	v_mfma_f32_16x16x32_bf16 v[28:31], v[148:151], v[222:225], v[28:31]
	v_mfma_f32_16x16x32_bf16 v[24:27], v[156:159], v[222:225], v[24:27]
	v_mfma_f32_16x16x32_bf16 v[12:15], v[148:151], v[230:233], v[12:15]
	v_mfma_f32_16x16x32_bf16 v[8:11], v[156:159], v[230:233], v[8:11]
	v_mfma_f32_16x16x32_bf16 v[60:63], v[152:155], v[210:213], v[60:63]
	v_mfma_f32_16x16x32_bf16 v[56:59], v[182:185], v[210:213], v[56:59]
	v_mfma_f32_16x16x32_bf16 v[44:47], v[152:155], v[218:221], v[44:47]
	v_mfma_f32_16x16x32_bf16 v[40:43], v[182:185], v[218:221], v[40:43]
	v_mfma_f32_16x16x32_bf16 v[28:31], v[152:155], v[226:229], v[28:31]
	v_mfma_f32_16x16x32_bf16 v[24:27], v[182:185], v[226:229], v[24:27]
	v_mfma_f32_16x16x32_bf16 v[12:15], v[152:155], v[234:237], v[12:15]
	v_mfma_f32_16x16x32_bf16 v[8:11], v[182:185], v[234:237], v[8:11]
	v_mfma_f32_16x16x32_bf16 v[52:55], v[186:189], v[202:205], v[52:55]
	v_mfma_f32_16x16x32_bf16 v[48:51], v[194:197], v[202:205], v[48:51]
	v_mfma_f32_16x16x32_bf16 v[36:39], v[186:189], v[214:217], v[36:39]
	v_mfma_f32_16x16x32_bf16 v[32:35], v[194:197], v[214:217], v[32:35]
	v_mfma_f32_16x16x32_bf16 v[20:23], v[186:189], v[222:225], v[20:23]
	v_mfma_f32_16x16x32_bf16 v[16:19], v[194:197], v[222:225], v[16:19]
	v_mfma_f32_16x16x32_bf16 v[4:7], v[186:189], v[230:233], v[4:7]
	v_mfma_f32_16x16x32_bf16 v[0:3], v[194:197], v[230:233], v[0:3]
	v_mfma_f32_16x16x32_bf16 v[52:55], v[190:193], v[210:213], v[52:55]
	v_mfma_f32_16x16x32_bf16 v[48:51], v[198:201], v[210:213], v[48:51]
	v_mfma_f32_16x16x32_bf16 v[36:39], v[190:193], v[218:221], v[36:39]
	v_mfma_f32_16x16x32_bf16 v[32:35], v[198:201], v[218:221], v[32:35]
	v_mfma_f32_16x16x32_bf16 v[20:23], v[190:193], v[226:229], v[20:23]
	v_mfma_f32_16x16x32_bf16 v[16:19], v[198:201], v[226:229], v[16:19]
	v_mfma_f32_16x16x32_bf16 v[4:7], v[190:193], v[234:237], v[4:7]
	v_mfma_f32_16x16x32_bf16 v[0:3], v[198:201], v[234:237], v[0:3]
	s_setprio 0
	s_barrier
	s_add_i32 s65, 0, 0x18000
	v_add_u32_e32 v138, s65, v166
	s_add_i32 s66, 0, 0x1c000
	ds_read_b128 v[148:151], v138
	ds_read_b128 v[152:155], v138 offset:1024
	ds_read_b128 v[156:159], v138 offset:2048
	ds_read_b128 v[182:185], v138 offset:3072
	v_add_u32_e32 v138, s66, v166
	ds_read_b128 v[186:189], v138
	ds_read_b128 v[190:193], v138 offset:1024
	ds_read_b128 v[194:197], v138 offset:2048
	ds_read_b128 v[198:201], v138 offset:3072
	s_add_u32 s38, s38, 0x80000
	s_addc_u32 s39, s39, 0
	s_mov_b32 m0, s43
	v_lshl_add_u64 v[242:243], s[38:39], 0, v[130:131]
	ds_read_b128 v[202:205], v180 offset:32768
	ds_read_b128 v[210:213], v180 offset:33792
	ds_read_b128 v[214:217], v180 offset:34816
	ds_read_b128 v[218:221], v180 offset:35840
	ds_read_b128 v[222:225], v180 offset:36864
	ds_read_b128 v[226:229], v180 offset:37888
	ds_read_b128 v[230:233], v180 offset:38912
	ds_read_b128 v[234:237], v180 offset:39936
	global_load_lds_dwordx4 v[242:243], off
	v_lshl_add_u64 v[242:243], s[38:39], 0, v[134:135]
	s_mov_b32 m0, s44
	s_nop 0
	global_load_lds_dwordx4 v[242:243], off
	s_waitcnt vmcnt(8)
	s_waitcnt lgkmcnt(0)
	s_barrier
	s_setprio 1
	v_mfma_f32_16x16x32_bf16 v[124:127], v[148:151], v[202:205], v[124:127]
	v_mfma_f32_16x16x32_bf16 v[120:123], v[156:159], v[202:205], v[120:123]
	v_mfma_f32_16x16x32_bf16 v[108:111], v[148:151], v[214:217], v[108:111]
	v_mfma_f32_16x16x32_bf16 v[104:107], v[156:159], v[214:217], v[104:107]
	v_mfma_f32_16x16x32_bf16 v[92:95], v[148:151], v[222:225], v[92:95]
	v_mfma_f32_16x16x32_bf16 v[88:91], v[156:159], v[222:225], v[88:91]
	v_mfma_f32_16x16x32_bf16 v[76:79], v[148:151], v[230:233], v[76:79]
	v_mfma_f32_16x16x32_bf16 v[72:75], v[156:159], v[230:233], v[72:75]
	v_mfma_f32_16x16x32_bf16 v[124:127], v[152:155], v[210:213], v[124:127]
	v_mfma_f32_16x16x32_bf16 v[120:123], v[182:185], v[210:213], v[120:123]
	v_mfma_f32_16x16x32_bf16 v[108:111], v[152:155], v[218:221], v[108:111]
	v_mfma_f32_16x16x32_bf16 v[104:107], v[182:185], v[218:221], v[104:107]
	v_mfma_f32_16x16x32_bf16 v[92:95], v[152:155], v[226:229], v[92:95]
	v_mfma_f32_16x16x32_bf16 v[88:91], v[182:185], v[226:229], v[88:91]
	v_mfma_f32_16x16x32_bf16 v[76:79], v[152:155], v[234:237], v[76:79]
	v_mfma_f32_16x16x32_bf16 v[72:75], v[182:185], v[234:237], v[72:75]
	v_mfma_f32_16x16x32_bf16 v[116:119], v[186:189], v[202:205], v[116:119]
	v_mfma_f32_16x16x32_bf16 v[112:115], v[194:197], v[202:205], v[112:115]
	v_mfma_f32_16x16x32_bf16 v[100:103], v[186:189], v[214:217], v[100:103]
	v_mfma_f32_16x16x32_bf16 v[96:99], v[194:197], v[214:217], v[96:99]
	v_mfma_f32_16x16x32_bf16 v[84:87], v[186:189], v[222:225], v[84:87]
	v_mfma_f32_16x16x32_bf16 v[80:83], v[194:197], v[222:225], v[80:83]
	v_mfma_f32_16x16x32_bf16 v[68:71], v[186:189], v[230:233], v[68:71]
	v_mfma_f32_16x16x32_bf16 v[64:67], v[194:197], v[230:233], v[64:67]
	v_mfma_f32_16x16x32_bf16 v[116:119], v[190:193], v[210:213], v[116:119]
	v_mfma_f32_16x16x32_bf16 v[112:115], v[198:201], v[210:213], v[112:115]
	v_mfma_f32_16x16x32_bf16 v[100:103], v[190:193], v[218:221], v[100:103]
	v_mfma_f32_16x16x32_bf16 v[96:99], v[198:201], v[218:221], v[96:99]
	v_mfma_f32_16x16x32_bf16 v[84:87], v[190:193], v[226:229], v[84:87]
	v_mfma_f32_16x16x32_bf16 v[80:83], v[198:201], v[226:229], v[80:83]
	v_mfma_f32_16x16x32_bf16 v[68:71], v[190:193], v[234:237], v[68:71]
	v_mfma_f32_16x16x32_bf16 v[64:67], v[198:201], v[234:237], v[64:67]
	s_setprio 0
	s_barrier
	s_add_i32 s38, s65, s41
	v_lshl_add_u64 v[160:161], v[160:161], 0, s[18:19]
	s_mov_b32 m0, s38
	ds_read_b128 v[202:205], v180 offset:49152
	ds_read_b128 v[210:213], v180 offset:50176
	ds_read_b128 v[214:217], v180 offset:51200
	ds_read_b128 v[218:221], v180 offset:52224
	ds_read_b128 v[222:225], v180 offset:53248
	ds_read_b128 v[226:229], v180 offset:54272
	ds_read_b128 v[230:233], v180 offset:55296
	ds_read_b128 v[234:237], v180 offset:56320
	global_load_lds_dwordx4 v[160:161], off
	s_add_i32 m0, s38, 0x2000
	s_add_u32 s36, s36, 0x80080
	v_lshl_add_u64 v[160:161], v[206:207], 0, s[18:19]
	s_addc_u32 s37, s37, 0
	s_add_i32 s38, s66, s41
	global_load_lds_dwordx4 v[160:161], off
	v_lshl_add_u64 v[160:161], s[36:37], 0, v[132:133]
	s_mov_b32 m0, s38
	s_nop 0
	global_load_lds_dwordx4 v[160:161], off
	v_lshl_add_u64 v[160:161], s[36:37], 0, v[136:137]
	s_add_i32 m0, s38, 0x2000
	s_nop 0
	global_load_lds_dwordx4 v[160:161], off
	v_lshl_add_u64 v[160:161], v[238:239], 0, s[18:19]
	s_mov_b32 m0, s45
	s_nop 0
	global_load_lds_dwordx4 v[160:161], off
	v_lshl_add_u64 v[160:161], v[240:241], 0, s[18:19]
	s_mov_b32 m0, s46
	s_nop 0
	global_load_lds_dwordx4 v[160:161], off
	s_waitcnt vmcnt(8)
	s_waitcnt lgkmcnt(0)
	s_barrier
	s_setprio 1
	v_mfma_f32_16x16x32_bf16 v[60:63], v[148:151], v[202:205], v[60:63]
	v_mfma_f32_16x16x32_bf16 v[56:59], v[156:159], v[202:205], v[56:59]
	v_mfma_f32_16x16x32_bf16 v[44:47], v[148:151], v[214:217], v[44:47]
	v_mfma_f32_16x16x32_bf16 v[40:43], v[156:159], v[214:217], v[40:43]
	v_mfma_f32_16x16x32_bf16 v[28:31], v[148:151], v[222:225], v[28:31]
	v_mfma_f32_16x16x32_bf16 v[24:27], v[156:159], v[222:225], v[24:27]
	v_mfma_f32_16x16x32_bf16 v[12:15], v[148:151], v[230:233], v[12:15]
	v_mfma_f32_16x16x32_bf16 v[8:11], v[156:159], v[230:233], v[8:11]
	v_mfma_f32_16x16x32_bf16 v[60:63], v[152:155], v[210:213], v[60:63]
	v_mfma_f32_16x16x32_bf16 v[56:59], v[182:185], v[210:213], v[56:59]
	v_mfma_f32_16x16x32_bf16 v[44:47], v[152:155], v[218:221], v[44:47]
	v_mfma_f32_16x16x32_bf16 v[40:43], v[182:185], v[218:221], v[40:43]
	v_mfma_f32_16x16x32_bf16 v[28:31], v[152:155], v[226:229], v[28:31]
	v_mfma_f32_16x16x32_bf16 v[24:27], v[182:185], v[226:229], v[24:27]
	v_mfma_f32_16x16x32_bf16 v[12:15], v[152:155], v[234:237], v[12:15]
	v_mfma_f32_16x16x32_bf16 v[8:11], v[182:185], v[234:237], v[8:11]
	v_mfma_f32_16x16x32_bf16 v[52:55], v[186:189], v[202:205], v[52:55]
	v_mfma_f32_16x16x32_bf16 v[48:51], v[194:197], v[202:205], v[48:51]
	v_mfma_f32_16x16x32_bf16 v[36:39], v[186:189], v[214:217], v[36:39]
	v_mfma_f32_16x16x32_bf16 v[32:35], v[194:197], v[214:217], v[32:35]
	v_mfma_f32_16x16x32_bf16 v[20:23], v[186:189], v[222:225], v[20:23]
	v_mfma_f32_16x16x32_bf16 v[16:19], v[194:197], v[222:225], v[16:19]
	v_mfma_f32_16x16x32_bf16 v[4:7], v[186:189], v[230:233], v[4:7]
	v_mfma_f32_16x16x32_bf16 v[0:3], v[194:197], v[230:233], v[0:3]
	v_mfma_f32_16x16x32_bf16 v[52:55], v[190:193], v[210:213], v[52:55]
	v_mfma_f32_16x16x32_bf16 v[48:51], v[198:201], v[210:213], v[48:51]
	v_mfma_f32_16x16x32_bf16 v[36:39], v[190:193], v[218:221], v[36:39]
	v_mfma_f32_16x16x32_bf16 v[32:35], v[198:201], v[218:221], v[32:35]
	v_mfma_f32_16x16x32_bf16 v[20:23], v[190:193], v[226:229], v[20:23]
	v_mfma_f32_16x16x32_bf16 v[16:19], v[198:201], v[226:229], v[16:19]
	v_mfma_f32_16x16x32_bf16 v[4:7], v[190:193], v[234:237], v[4:7]
	v_mfma_f32_16x16x32_bf16 v[0:3], v[198:201], v[234:237], v[0:3]
	s_setprio 0
	s_barrier
	s_add_i32 s64, s64, 2
	s_add_u32 s34, s34, 0x100
	s_addc_u32 s35, s35, 0
	s_add_u32 s25, s25, 0x100
	s_addc_u32 s63, s63, 0
	s_cmp_gt_u32 s64, 29
	s_cbranch_scc0 .LBB0_163
	s_and_b64 vcc, exec, s[20:21]
	s_cbranch_vccz .LBB0_166
	s_barrier

.LBB0_321:
	s_add_u32 s29, s34, s27
	s_addc_u32 s31, s35, 0
	s_add_u32 s41, s29, 0x100
	s_addc_u32 s48, s31, 0
	s_and_b64 s[46:47], s[44:45], exec
	s_cselect_b32 s49, s37, s48
	s_cselect_b32 s48, s36, s41
	s_add_u32 s27, s24, s27
	s_addc_u32 s41, s25, 0
	s_add_u32 s27, s27, 0x100
	s_addc_u32 s41, s41, 0
	s_and_b64 s[44:45], s[44:45], exec
	s_cselect_b32 s51, s39, s41
	s_cselect_b32 s50, s38, s27
	s_add_u32 s54, s29, 0x80080
	s_addc_u32 s55, s31, 0
	s_add_i32 s74, s66, s2
	ds_read_b128 v[144:147], v129
	ds_read_b128 v[148:151], v129 offset:1024
	ds_read_b128 v[152:155], v129 offset:2048
	ds_read_b128 v[156:159], v129 offset:3072
	ds_read_b128 v[164:167], v141
	ds_read_b128 v[168:171], v141 offset:1024
	ds_read_b128 v[172:175], v141 offset:2048
	ds_read_b128 v[180:183], v141 offset:3072
	s_add_i32 m0, s3, 0xc000
	s_add_i32 s75, s3, 0xe000
	s_add_i32 s71, s74, 0x2000
	s_add_u32 s52, s50, 0x80000
	s_addc_u32 s53, s51, 0
	s_add_i32 s73, s67, s2
	s_add_i32 s72, s73, 0x2000
	s_add_i32 s70, 0, 0x18000
	s_add_i32 s69, 0, 0x1c000
	s_add_u32 s46, s48, 0x80000
	s_addc_u32 s47, s49, 0
	s_add_i32 s41, s70, s2
	s_add_i32 s29, s41, 0x2000
	s_add_u32 s44, s50, 0x80080
	s_addc_u32 s45, s51, 0
	s_add_i32 s31, s69, s2
	s_add_i32 s27, s31, 0x2000
	v_lshl_add_u64 v[160:161], s[54:55], 0, v[130:131]
	ds_read_b128 v[184:187], v142
	ds_read_b128 v[188:191], v142 offset:1024
	ds_read_b128 v[192:195], v142 offset:2048
	ds_read_b128 v[196:199], v142 offset:3072
	ds_read_b128 v[200:203], v142 offset:4096
	ds_read_b128 v[204:207], v142 offset:5120
	ds_read_b128 v[210:213], v142 offset:6144
	ds_read_b128 v[214:217], v142 offset:7168
	global_load_lds_dwordx4 v[160:161], off
	v_lshl_add_u64 v[160:161], s[54:55], 0, v[134:135]
	s_mov_b32 m0, s75
	s_nop 0
	global_load_lds_dwordx4 v[160:161], off
	s_waitcnt vmcnt(8)
	s_waitcnt lgkmcnt(0)
	s_barrier
	s_setprio 1
	v_mfma_f32_16x16x32_bf16 v[124:127], v[144:147], v[184:187], v[124:127]
	v_mfma_f32_16x16x32_bf16 v[120:123], v[152:155], v[184:187], v[120:123]
	v_mfma_f32_16x16x32_bf16 v[116:119], v[144:147], v[192:195], v[116:119]
	v_mfma_f32_16x16x32_bf16 v[112:115], v[152:155], v[192:195], v[112:115]
	v_mfma_f32_16x16x32_bf16 v[108:111], v[144:147], v[200:203], v[108:111]
	v_mfma_f32_16x16x32_bf16 v[104:107], v[152:155], v[200:203], v[104:107]
	v_mfma_f32_16x16x32_bf16 v[100:103], v[144:147], v[210:213], v[100:103]
	v_mfma_f32_16x16x32_bf16 v[96:99], v[152:155], v[210:213], v[96:99]
	v_mfma_f32_16x16x32_bf16 v[124:127], v[148:151], v[188:191], v[124:127]
	v_mfma_f32_16x16x32_bf16 v[120:123], v[156:159], v[188:191], v[120:123]
	v_mfma_f32_16x16x32_bf16 v[116:119], v[148:151], v[196:199], v[116:119]
	v_mfma_f32_16x16x32_bf16 v[112:115], v[156:159], v[196:199], v[112:115]
	v_mfma_f32_16x16x32_bf16 v[108:111], v[148:151], v[204:207], v[108:111]
	v_mfma_f32_16x16x32_bf16 v[104:107], v[156:159], v[204:207], v[104:107]
	v_mfma_f32_16x16x32_bf16 v[100:103], v[148:151], v[214:217], v[100:103]
	v_mfma_f32_16x16x32_bf16 v[96:99], v[156:159], v[214:217], v[96:99]
	v_mfma_f32_16x16x32_bf16 v[92:95], v[164:167], v[184:187], v[92:95]
	v_mfma_f32_16x16x32_bf16 v[88:91], v[172:175], v[184:187], v[88:91]
	v_mfma_f32_16x16x32_bf16 v[84:87], v[164:167], v[192:195], v[84:87]
	v_mfma_f32_16x16x32_bf16 v[80:83], v[172:175], v[192:195], v[80:83]
	v_mfma_f32_16x16x32_bf16 v[76:79], v[164:167], v[200:203], v[76:79]
	v_mfma_f32_16x16x32_bf16 v[72:75], v[172:175], v[200:203], v[72:75]
	v_mfma_f32_16x16x32_bf16 v[68:71], v[164:167], v[210:213], v[68:71]
	v_mfma_f32_16x16x32_bf16 v[64:67], v[172:175], v[210:213], v[64:67]
	v_mfma_f32_16x16x32_bf16 v[92:95], v[168:171], v[188:191], v[92:95]
	v_mfma_f32_16x16x32_bf16 v[88:91], v[180:183], v[188:191], v[88:91]
	v_mfma_f32_16x16x32_bf16 v[84:87], v[168:171], v[196:199], v[84:87]
	v_mfma_f32_16x16x32_bf16 v[80:83], v[180:183], v[196:199], v[80:83]
	v_mfma_f32_16x16x32_bf16 v[76:79], v[168:171], v[204:207], v[76:79]
	v_mfma_f32_16x16x32_bf16 v[72:75], v[180:183], v[204:207], v[72:75]
	v_mfma_f32_16x16x32_bf16 v[68:71], v[168:171], v[214:217], v[68:71]
	v_mfma_f32_16x16x32_bf16 v[64:67], v[180:183], v[214:217], v[64:67]
	s_setprio 0
	s_barrier
	s_mov_b32 m0, s74
	v_lshl_add_u64 v[160:161], s[50:51], 0, v[132:133]
	ds_read_b128 v[184:187], v142 offset:16384
	ds_read_b128 v[188:191], v142 offset:17408
	ds_read_b128 v[192:195], v142 offset:18432
	ds_read_b128 v[196:199], v142 offset:19456
	ds_read_b128 v[200:203], v142 offset:20480
	ds_read_b128 v[204:207], v142 offset:21504
	ds_read_b128 v[210:213], v142 offset:22528
	ds_read_b128 v[214:217], v142 offset:23552
	global_load_lds_dwordx4 v[160:161], off
	v_lshl_add_u64 v[176:177], s[50:51], 0, v[136:137]
	s_mov_b32 m0, s71
	v_lshl_add_u64 v[218:219], s[52:53], 0, v[132:133]
	global_load_lds_dwordx4 v[176:177], off
	s_mov_b32 m0, s73
	v_lshl_add_u64 v[220:221], s[48:49], 0, v[134:135]
	global_load_lds_dwordx4 v[218:219], off
	v_lshl_add_u64 v[218:219], s[52:53], 0, v[136:137]
	s_mov_b32 m0, s72
	s_nop 0
	global_load_lds_dwordx4 v[218:219], off
	v_lshl_add_u64 v[218:219], s[48:49], 0, v[130:131]
	s_mov_b32 m0, s3
	s_nop 0
	global_load_lds_dwordx4 v[218:219], off
	s_mov_b32 m0, s60
	s_nop 0
	global_load_lds_dwordx4 v[220:221], off
	s_waitcnt vmcnt(8)
	s_waitcnt lgkmcnt(0)
	s_barrier
	s_setprio 1
	v_mfma_f32_16x16x32_bf16 v[60:63], v[144:147], v[184:187], v[60:63]
	v_mfma_f32_16x16x32_bf16 v[56:59], v[152:155], v[184:187], v[56:59]
	v_mfma_f32_16x16x32_bf16 v[52:55], v[144:147], v[192:195], v[52:55]
	v_mfma_f32_16x16x32_bf16 v[48:51], v[152:155], v[192:195], v[48:51]
	v_mfma_f32_16x16x32_bf16 v[44:47], v[144:147], v[200:203], v[44:47]
	v_mfma_f32_16x16x32_bf16 v[40:43], v[152:155], v[200:203], v[40:43]
	v_mfma_f32_16x16x32_bf16 v[36:39], v[144:147], v[210:213], v[36:39]
	v_mfma_f32_16x16x32_bf16 v[32:35], v[152:155], v[210:213], v[32:35]
	v_mfma_f32_16x16x32_bf16 v[60:63], v[148:151], v[188:191], v[60:63]
	v_mfma_f32_16x16x32_bf16 v[56:59], v[156:159], v[188:191], v[56:59]
	v_mfma_f32_16x16x32_bf16 v[52:55], v[148:151], v[196:199], v[52:55]
	v_mfma_f32_16x16x32_bf16 v[48:51], v[156:159], v[196:199], v[48:51]
	v_mfma_f32_16x16x32_bf16 v[44:47], v[148:151], v[204:207], v[44:47]
	v_mfma_f32_16x16x32_bf16 v[40:43], v[156:159], v[204:207], v[40:43]
	v_mfma_f32_16x16x32_bf16 v[36:39], v[148:151], v[214:217], v[36:39]
	v_mfma_f32_16x16x32_bf16 v[32:35], v[156:159], v[214:217], v[32:35]
	v_mfma_f32_16x16x32_bf16 v[28:31], v[164:167], v[184:187], v[28:31]
	v_mfma_f32_16x16x32_bf16 v[24:27], v[172:175], v[184:187], v[24:27]
	v_mfma_f32_16x16x32_bf16 v[20:23], v[164:167], v[192:195], v[20:23]
	v_mfma_f32_16x16x32_bf16 v[16:19], v[172:175], v[192:195], v[16:19]
	v_mfma_f32_16x16x32_bf16 v[12:15], v[164:167], v[200:203], v[12:15]
	v_mfma_f32_16x16x32_bf16 v[8:11], v[172:175], v[200:203], v[8:11]
	v_mfma_f32_16x16x32_bf16 v[4:7], v[164:167], v[210:213], v[4:7]
	v_mfma_f32_16x16x32_bf16 v[0:3], v[172:175], v[210:213], v[0:3]
	v_mfma_f32_16x16x32_bf16 v[28:31], v[168:171], v[188:191], v[28:31]
	v_mfma_f32_16x16x32_bf16 v[24:27], v[180:183], v[188:191], v[24:27]
	v_mfma_f32_16x16x32_bf16 v[20:23], v[168:171], v[196:199], v[20:23]
	v_mfma_f32_16x16x32_bf16 v[16:19], v[180:183], v[196:199], v[16:19]
	v_mfma_f32_16x16x32_bf16 v[12:15], v[168:171], v[204:207], v[12:15]
	v_mfma_f32_16x16x32_bf16 v[8:11], v[180:183], v[204:207], v[8:11]
	v_mfma_f32_16x16x32_bf16 v[4:7], v[168:171], v[214:217], v[4:7]
	v_mfma_f32_16x16x32_bf16 v[0:3], v[180:183], v[214:217], v[0:3]
	s_setprio 0
	s_barrier
	v_add_u32_e32 v143, s70, v140
	ds_read_b128 v[144:147], v143
	ds_read_b128 v[148:151], v143 offset:1024
	ds_read_b128 v[152:155], v143 offset:2048
	ds_read_b128 v[156:159], v143 offset:3072
	v_add_u32_e32 v143, s69, v140
	ds_read_b128 v[164:167], v143
	ds_read_b128 v[168:171], v143 offset:1024
	ds_read_b128 v[172:175], v143 offset:2048
	ds_read_b128 v[180:183], v143 offset:3072
	s_mov_b32 m0, s61
	v_lshl_add_u64 v[222:223], s[46:47], 0, v[130:131]
	ds_read_b128 v[184:187], v142 offset:32768
	ds_read_b128 v[188:191], v142 offset:33792
	ds_read_b128 v[192:195], v142 offset:34816
	ds_read_b128 v[196:199], v142 offset:35840
	ds_read_b128 v[200:203], v142 offset:36864
	ds_read_b128 v[204:207], v142 offset:37888
	ds_read_b128 v[210:213], v142 offset:38912
	ds_read_b128 v[214:217], v142 offset:39936
	global_load_lds_dwordx4 v[222:223], off
	v_lshl_add_u64 v[222:223], s[46:47], 0, v[134:135]
	s_mov_b32 m0, s62
	s_nop 0
	global_load_lds_dwordx4 v[222:223], off
	s_waitcnt vmcnt(8)
	s_waitcnt lgkmcnt(0)
	s_barrier
	s_setprio 1
	v_mfma_f32_16x16x32_bf16 v[124:127], v[144:147], v[184:187], v[124:127]
	v_mfma_f32_16x16x32_bf16 v[120:123], v[152:155], v[184:187], v[120:123]
	v_mfma_f32_16x16x32_bf16 v[116:119], v[144:147], v[192:195], v[116:119]
	v_mfma_f32_16x16x32_bf16 v[112:115], v[152:155], v[192:195], v[112:115]
	v_mfma_f32_16x16x32_bf16 v[108:111], v[144:147], v[200:203], v[108:111]
	v_mfma_f32_16x16x32_bf16 v[104:107], v[152:155], v[200:203], v[104:107]
	v_mfma_f32_16x16x32_bf16 v[100:103], v[144:147], v[210:213], v[100:103]
	v_mfma_f32_16x16x32_bf16 v[96:99], v[152:155], v[210:213], v[96:99]
	v_mfma_f32_16x16x32_bf16 v[124:127], v[148:151], v[188:191], v[124:127]
	v_mfma_f32_16x16x32_bf16 v[120:123], v[156:159], v[188:191], v[120:123]
	v_mfma_f32_16x16x32_bf16 v[116:119], v[148:151], v[196:199], v[116:119]
	v_mfma_f32_16x16x32_bf16 v[112:115], v[156:159], v[196:199], v[112:115]
	v_mfma_f32_16x16x32_bf16 v[108:111], v[148:151], v[204:207], v[108:111]
	v_mfma_f32_16x16x32_bf16 v[104:107], v[156:159], v[204:207], v[104:107]
	v_mfma_f32_16x16x32_bf16 v[100:103], v[148:151], v[214:217], v[100:103]
	v_mfma_f32_16x16x32_bf16 v[96:99], v[156:159], v[214:217], v[96:99]
	v_mfma_f32_16x16x32_bf16 v[92:95], v[164:167], v[184:187], v[92:95]
	v_mfma_f32_16x16x32_bf16 v[88:91], v[172:175], v[184:187], v[88:91]
	v_mfma_f32_16x16x32_bf16 v[84:87], v[164:167], v[192:195], v[84:87]
	v_mfma_f32_16x16x32_bf16 v[80:83], v[172:175], v[192:195], v[80:83]
	v_mfma_f32_16x16x32_bf16 v[76:79], v[164:167], v[200:203], v[76:79]
	v_mfma_f32_16x16x32_bf16 v[72:75], v[172:175], v[200:203], v[72:75]
	v_mfma_f32_16x16x32_bf16 v[68:71], v[164:167], v[210:213], v[68:71]
	v_mfma_f32_16x16x32_bf16 v[64:67], v[172:175], v[210:213], v[64:67]
	v_mfma_f32_16x16x32_bf16 v[92:95], v[168:171], v[188:191], v[92:95]
	v_mfma_f32_16x16x32_bf16 v[88:91], v[180:183], v[188:191], v[88:91]
	v_mfma_f32_16x16x32_bf16 v[84:87], v[168:171], v[196:199], v[84:87]
	v_mfma_f32_16x16x32_bf16 v[80:83], v[180:183], v[196:199], v[80:83]
	v_mfma_f32_16x16x32_bf16 v[76:79], v[168:171], v[204:207], v[76:79]
	v_mfma_f32_16x16x32_bf16 v[72:75], v[180:183], v[204:207], v[72:75]
	v_mfma_f32_16x16x32_bf16 v[68:71], v[168:171], v[214:217], v[68:71]
	v_mfma_f32_16x16x32_bf16 v[64:67], v[180:183], v[214:217], v[64:67]
	s_setprio 0
	s_barrier
	s_mov_b32 m0, s41
	v_lshl_add_u64 v[160:161], v[160:161], 0, s[20:21]
	ds_read_b128 v[184:187], v142 offset:49152
	ds_read_b128 v[188:191], v142 offset:50176
	ds_read_b128 v[192:195], v142 offset:51200
	ds_read_b128 v[196:199], v142 offset:52224
	ds_read_b128 v[200:203], v142 offset:53248
	ds_read_b128 v[204:207], v142 offset:54272
	ds_read_b128 v[210:213], v142 offset:55296
	ds_read_b128 v[214:217], v142 offset:56320
	global_load_lds_dwordx4 v[160:161], off
	v_lshl_add_u64 v[160:161], v[176:177], 0, s[20:21]
	s_mov_b32 m0, s29
	s_nop 0
	global_load_lds_dwordx4 v[160:161], off
	v_lshl_add_u64 v[160:161], s[44:45], 0, v[132:133]
	s_mov_b32 m0, s31
	s_nop 0
	global_load_lds_dwordx4 v[160:161], off
	v_lshl_add_u64 v[160:161], s[44:45], 0, v[136:137]
	s_mov_b32 m0, s27
	s_nop 0
	global_load_lds_dwordx4 v[160:161], off
	v_lshl_add_u64 v[160:161], v[218:219], 0, s[20:21]
	s_mov_b32 m0, s64
	s_nop 0
	global_load_lds_dwordx4 v[160:161], off
	v_lshl_add_u64 v[160:161], v[220:221], 0, s[20:21]
	s_mov_b32 m0, s65
	s_nop 0
	global_load_lds_dwordx4 v[160:161], off
	s_waitcnt vmcnt(8)
	s_waitcnt lgkmcnt(0)
	s_barrier
	s_setprio 1
	v_mfma_f32_16x16x32_bf16 v[60:63], v[144:147], v[184:187], v[60:63]
	v_mfma_f32_16x16x32_bf16 v[56:59], v[152:155], v[184:187], v[56:59]
	v_mfma_f32_16x16x32_bf16 v[52:55], v[144:147], v[192:195], v[52:55]
	v_mfma_f32_16x16x32_bf16 v[48:51], v[152:155], v[192:195], v[48:51]
	v_mfma_f32_16x16x32_bf16 v[44:47], v[144:147], v[200:203], v[44:47]
	v_mfma_f32_16x16x32_bf16 v[40:43], v[152:155], v[200:203], v[40:43]
	v_mfma_f32_16x16x32_bf16 v[36:39], v[144:147], v[210:213], v[36:39]
	v_mfma_f32_16x16x32_bf16 v[32:35], v[152:155], v[210:213], v[32:35]
	v_mfma_f32_16x16x32_bf16 v[60:63], v[148:151], v[188:191], v[60:63]
	v_mfma_f32_16x16x32_bf16 v[56:59], v[156:159], v[188:191], v[56:59]
	v_mfma_f32_16x16x32_bf16 v[52:55], v[148:151], v[196:199], v[52:55]
	v_mfma_f32_16x16x32_bf16 v[48:51], v[156:159], v[196:199], v[48:51]
	v_mfma_f32_16x16x32_bf16 v[44:47], v[148:151], v[204:207], v[44:47]
	v_mfma_f32_16x16x32_bf16 v[40:43], v[156:159], v[204:207], v[40:43]
	v_mfma_f32_16x16x32_bf16 v[36:39], v[148:151], v[214:217], v[36:39]
	v_mfma_f32_16x16x32_bf16 v[32:35], v[156:159], v[214:217], v[32:35]
	v_mfma_f32_16x16x32_bf16 v[28:31], v[164:167], v[184:187], v[28:31]
	v_mfma_f32_16x16x32_bf16 v[24:27], v[172:175], v[184:187], v[24:27]
	v_mfma_f32_16x16x32_bf16 v[20:23], v[164:167], v[192:195], v[20:23]
	v_mfma_f32_16x16x32_bf16 v[16:19], v[172:175], v[192:195], v[16:19]
	v_mfma_f32_16x16x32_bf16 v[12:15], v[164:167], v[200:203], v[12:15]
	v_mfma_f32_16x16x32_bf16 v[8:11], v[172:175], v[200:203], v[8:11]
	v_mfma_f32_16x16x32_bf16 v[4:7], v[164:167], v[210:213], v[4:7]
	v_mfma_f32_16x16x32_bf16 v[0:3], v[172:175], v[210:213], v[0:3]
	v_mfma_f32_16x16x32_bf16 v[28:31], v[168:171], v[188:191], v[28:31]
	v_mfma_f32_16x16x32_bf16 v[24:27], v[180:183], v[188:191], v[24:27]
	v_mfma_f32_16x16x32_bf16 v[20:23], v[168:171], v[196:199], v[20:23]
	v_mfma_f32_16x16x32_bf16 v[16:19], v[180:183], v[196:199], v[16:19]
	v_mfma_f32_16x16x32_bf16 v[12:15], v[168:171], v[204:207], v[12:15]
	v_mfma_f32_16x16x32_bf16 v[8:11], v[180:183], v[204:207], v[8:11]
	v_mfma_f32_16x16x32_bf16 v[4:7], v[168:171], v[214:217], v[4:7]
	v_mfma_f32_16x16x32_bf16 v[0:3], v[180:183], v[214:217], v[0:3]
	s_setprio 0
	s_barrier
	s_movk_i32 s27, 0x100
	s_andn2_b64 vcc, exec, s[42:43]
	s_mov_b64 s[44:45], -1
	s_mov_b64 s[42:43], 0
	s_cbranch_vccz .LBB0_321
	s_and_b64 vcc, exec, s[22:23]
	s_cbranch_vccz .LBB0_324
	s_barrier

.LBB0_965:
	ds_read_b128 v[128:131], v169
	ds_read_b128 v[132:135], v169 offset:1024
	ds_read_b128 v[154:157], v169 offset:2048
	ds_read_b128 v[158:161], v169 offset:3072
	ds_read_b128 v[172:175], v170
	ds_read_b128 v[180:183], v170 offset:1024
	ds_read_b128 v[184:187], v170 offset:2048
	ds_read_b128 v[188:191], v170 offset:3072
	s_add_u32 s30, s28, 0xfff80080
	s_addc_u32 s31, s29, -1
	s_cmp_eq_u32 s57, 28
	s_cselect_b32 s35, s2, s31
	s_cselect_b32 s34, s3, s30
	s_cselect_b32 s31, s17, s27
	s_cselect_b32 s30, s19, s25
	v_lshl_add_u64 v[162:163], s[28:29], 0, v[148:149]
	s_add_i32 m0, s38, 0xc000
	ds_read_b128 v[192:195], v171
	ds_read_b128 v[196:199], v171 offset:1024
	ds_read_b128 v[200:203], v171 offset:2048
	ds_read_b128 v[204:207], v171 offset:3072
	ds_read_b128 v[210:213], v171 offset:4096
	ds_read_b128 v[214:217], v171 offset:5120
	ds_read_b128 v[218:221], v171 offset:6144
	ds_read_b128 v[222:225], v171 offset:7168
	global_load_lds_dwordx4 v[162:163], off
	v_lshl_add_u64 v[162:163], s[28:29], 0, v[150:151]
	s_add_i32 m0, s38, 0xe000
	s_nop 0
	global_load_lds_dwordx4 v[162:163], off
	s_waitcnt vmcnt(8)
	s_waitcnt lgkmcnt(0)
	s_barrier
	s_setprio 1
	v_mfma_f32_16x16x32_bf16 v[124:127], v[128:131], v[192:195], v[124:127]
	v_mfma_f32_16x16x32_bf16 v[120:123], v[154:157], v[192:195], v[120:123]
	v_mfma_f32_16x16x32_bf16 v[108:111], v[128:131], v[200:203], v[108:111]
	v_mfma_f32_16x16x32_bf16 v[104:107], v[154:157], v[200:203], v[104:107]
	v_mfma_f32_16x16x32_bf16 v[92:95], v[128:131], v[210:213], v[92:95]
	v_mfma_f32_16x16x32_bf16 v[88:91], v[154:157], v[210:213], v[88:91]
	v_mfma_f32_16x16x32_bf16 v[76:79], v[128:131], v[218:221], v[76:79]
	v_mfma_f32_16x16x32_bf16 v[72:75], v[154:157], v[218:221], v[72:75]
	v_mfma_f32_16x16x32_bf16 v[124:127], v[132:135], v[196:199], v[124:127]
	v_mfma_f32_16x16x32_bf16 v[120:123], v[158:161], v[196:199], v[120:123]
	v_mfma_f32_16x16x32_bf16 v[108:111], v[132:135], v[204:207], v[108:111]
	v_mfma_f32_16x16x32_bf16 v[104:107], v[158:161], v[204:207], v[104:107]
	v_mfma_f32_16x16x32_bf16 v[92:95], v[132:135], v[214:217], v[92:95]
	v_mfma_f32_16x16x32_bf16 v[88:91], v[158:161], v[214:217], v[88:91]
	v_mfma_f32_16x16x32_bf16 v[76:79], v[132:135], v[222:225], v[76:79]
	v_mfma_f32_16x16x32_bf16 v[72:75], v[158:161], v[222:225], v[72:75]
	v_mfma_f32_16x16x32_bf16 v[116:119], v[172:175], v[192:195], v[116:119]
	v_mfma_f32_16x16x32_bf16 v[112:115], v[184:187], v[192:195], v[112:115]
	v_mfma_f32_16x16x32_bf16 v[100:103], v[172:175], v[200:203], v[100:103]
	v_mfma_f32_16x16x32_bf16 v[96:99], v[184:187], v[200:203], v[96:99]
	v_mfma_f32_16x16x32_bf16 v[84:87], v[172:175], v[210:213], v[84:87]
	v_mfma_f32_16x16x32_bf16 v[80:83], v[184:187], v[210:213], v[80:83]
	v_mfma_f32_16x16x32_bf16 v[68:71], v[172:175], v[218:221], v[68:71]
	v_mfma_f32_16x16x32_bf16 v[64:67], v[184:187], v[218:221], v[64:67]
	v_mfma_f32_16x16x32_bf16 v[116:119], v[180:183], v[196:199], v[116:119]
	v_mfma_f32_16x16x32_bf16 v[112:115], v[188:191], v[196:199], v[112:115]
	v_mfma_f32_16x16x32_bf16 v[100:103], v[180:183], v[204:207], v[100:103]
	v_mfma_f32_16x16x32_bf16 v[96:99], v[188:191], v[204:207], v[96:99]
	v_mfma_f32_16x16x32_bf16 v[84:87], v[180:183], v[214:217], v[84:87]
	v_mfma_f32_16x16x32_bf16 v[80:83], v[188:191], v[214:217], v[80:83]
	v_mfma_f32_16x16x32_bf16 v[68:71], v[180:183], v[222:225], v[68:71]
	v_mfma_f32_16x16x32_bf16 v[64:67], v[188:191], v[222:225], v[64:67]
	s_setprio 0
	s_barrier
	s_add_i32 s58, s47, s37
	v_lshl_add_u64 v[162:163], s[30:31], 0, v[140:141]
	s_mov_b32 m0, s58
	ds_read_b128 v[192:195], v171 offset:16384
	ds_read_b128 v[196:199], v171 offset:17408
	ds_read_b128 v[200:203], v171 offset:18432
	ds_read_b128 v[204:207], v171 offset:19456
	ds_read_b128 v[210:213], v171 offset:20480
	ds_read_b128 v[214:217], v171 offset:21504
	ds_read_b128 v[218:221], v171 offset:22528
	ds_read_b128 v[222:225], v171 offset:23552
	global_load_lds_dwordx4 v[162:163], off
	s_add_i32 m0, s58, 0x2000
	s_add_u32 s58, s30, 0x80000
	v_lshl_add_u64 v[176:177], s[30:31], 0, v[144:145]
	s_addc_u32 s59, s31, 0
	s_add_i32 s60, s48, s37
	global_load_lds_dwordx4 v[176:177], off
	v_lshl_add_u64 v[226:227], s[58:59], 0, v[140:141]
	s_mov_b32 m0, s60
	v_lshl_add_u64 v[228:229], s[34:35], 0, v[142:143]
	global_load_lds_dwordx4 v[226:227], off
	v_lshl_add_u64 v[226:227], s[58:59], 0, v[144:145]
	s_add_i32 m0, s60, 0x2000
	s_nop 0
	global_load_lds_dwordx4 v[226:227], off
	v_lshl_add_u64 v[226:227], s[34:35], 0, v[138:139]
	s_mov_b32 m0, s38
	s_nop 0
	global_load_lds_dwordx4 v[226:227], off
	s_mov_b32 m0, s39
	s_nop 0
	global_load_lds_dwordx4 v[228:229], off
	s_waitcnt vmcnt(8)
	s_waitcnt lgkmcnt(0)
	s_barrier
	s_setprio 1
	v_mfma_f32_16x16x32_bf16 v[60:63], v[128:131], v[192:195], v[60:63]
	v_mfma_f32_16x16x32_bf16 v[56:59], v[154:157], v[192:195], v[56:59]
	v_mfma_f32_16x16x32_bf16 v[44:47], v[128:131], v[200:203], v[44:47]
	v_mfma_f32_16x16x32_bf16 v[40:43], v[154:157], v[200:203], v[40:43]
	v_mfma_f32_16x16x32_bf16 v[28:31], v[128:131], v[210:213], v[28:31]
	v_mfma_f32_16x16x32_bf16 v[24:27], v[154:157], v[210:213], v[24:27]
	v_mfma_f32_16x16x32_bf16 v[12:15], v[128:131], v[218:221], v[12:15]
	v_mfma_f32_16x16x32_bf16 v[8:11], v[154:157], v[218:221], v[8:11]
	v_mfma_f32_16x16x32_bf16 v[60:63], v[132:135], v[196:199], v[60:63]
	v_mfma_f32_16x16x32_bf16 v[56:59], v[158:161], v[196:199], v[56:59]
	v_mfma_f32_16x16x32_bf16 v[44:47], v[132:135], v[204:207], v[44:47]
	v_mfma_f32_16x16x32_bf16 v[40:43], v[158:161], v[204:207], v[40:43]
	v_mfma_f32_16x16x32_bf16 v[28:31], v[132:135], v[214:217], v[28:31]
	v_mfma_f32_16x16x32_bf16 v[24:27], v[158:161], v[214:217], v[24:27]
	v_mfma_f32_16x16x32_bf16 v[12:15], v[132:135], v[222:225], v[12:15]
	v_mfma_f32_16x16x32_bf16 v[8:11], v[158:161], v[222:225], v[8:11]
	v_mfma_f32_16x16x32_bf16 v[52:55], v[172:175], v[192:195], v[52:55]
	v_mfma_f32_16x16x32_bf16 v[48:51], v[184:187], v[192:195], v[48:51]
	v_mfma_f32_16x16x32_bf16 v[36:39], v[172:175], v[200:203], v[36:39]
	v_mfma_f32_16x16x32_bf16 v[32:35], v[184:187], v[200:203], v[32:35]
	v_mfma_f32_16x16x32_bf16 v[20:23], v[172:175], v[210:213], v[20:23]
	v_mfma_f32_16x16x32_bf16 v[16:19], v[184:187], v[210:213], v[16:19]
	v_mfma_f32_16x16x32_bf16 v[4:7], v[172:175], v[218:221], v[4:7]
	v_mfma_f32_16x16x32_bf16 v[0:3], v[184:187], v[218:221], v[0:3]
	v_mfma_f32_16x16x32_bf16 v[52:55], v[180:183], v[196:199], v[52:55]
	v_mfma_f32_16x16x32_bf16 v[48:51], v[188:191], v[196:199], v[48:51]
	v_mfma_f32_16x16x32_bf16 v[36:39], v[180:183], v[204:207], v[36:39]
	v_mfma_f32_16x16x32_bf16 v[32:35], v[188:191], v[204:207], v[32:35]
	v_mfma_f32_16x16x32_bf16 v[20:23], v[180:183], v[214:217], v[20:23]
	v_mfma_f32_16x16x32_bf16 v[16:19], v[188:191], v[214:217], v[16:19]
	v_mfma_f32_16x16x32_bf16 v[4:7], v[180:183], v[222:225], v[4:7]
	v_mfma_f32_16x16x32_bf16 v[0:3], v[188:191], v[222:225], v[0:3]
	s_setprio 0
	s_barrier
	s_add_i32 s58, 0, 0x18000
	v_add_u32_e32 v146, s58, v167
	s_add_i32 s59, 0, 0x1c000
	ds_read_b128 v[128:131], v146
	ds_read_b128 v[132:135], v146 offset:1024
	ds_read_b128 v[154:157], v146 offset:2048
	ds_read_b128 v[158:161], v146 offset:3072
	v_add_u32_e32 v146, s59, v167
	ds_read_b128 v[172:175], v146
	ds_read_b128 v[180:183], v146 offset:1024
	ds_read_b128 v[184:187], v146 offset:2048
	ds_read_b128 v[188:191], v146 offset:3072
	s_add_u32 s34, s34, 0x80000
	s_addc_u32 s35, s35, 0
	s_mov_b32 m0, s40
	v_lshl_add_u64 v[230:231], s[34:35], 0, v[138:139]
	ds_read_b128 v[192:195], v171 offset:32768
	ds_read_b128 v[196:199], v171 offset:33792
	ds_read_b128 v[200:203], v171 offset:34816
	ds_read_b128 v[204:207], v171 offset:35840
	ds_read_b128 v[210:213], v171 offset:36864
	ds_read_b128 v[214:217], v171 offset:37888
	ds_read_b128 v[218:221], v171 offset:38912
	ds_read_b128 v[222:225], v171 offset:39936
	global_load_lds_dwordx4 v[230:231], off
	v_lshl_add_u64 v[230:231], s[34:35], 0, v[142:143]
	s_mov_b32 m0, s41
	s_nop 0
	global_load_lds_dwordx4 v[230:231], off
	s_waitcnt vmcnt(8)
	s_waitcnt lgkmcnt(0)
	s_barrier
	s_setprio 1
	v_mfma_f32_16x16x32_bf16 v[124:127], v[128:131], v[192:195], v[124:127]
	v_mfma_f32_16x16x32_bf16 v[120:123], v[154:157], v[192:195], v[120:123]
	v_mfma_f32_16x16x32_bf16 v[108:111], v[128:131], v[200:203], v[108:111]
	v_mfma_f32_16x16x32_bf16 v[104:107], v[154:157], v[200:203], v[104:107]
	v_mfma_f32_16x16x32_bf16 v[92:95], v[128:131], v[210:213], v[92:95]
	v_mfma_f32_16x16x32_bf16 v[88:91], v[154:157], v[210:213], v[88:91]
	v_mfma_f32_16x16x32_bf16 v[76:79], v[128:131], v[218:221], v[76:79]
	v_mfma_f32_16x16x32_bf16 v[72:75], v[154:157], v[218:221], v[72:75]
	v_mfma_f32_16x16x32_bf16 v[124:127], v[132:135], v[196:199], v[124:127]
	v_mfma_f32_16x16x32_bf16 v[120:123], v[158:161], v[196:199], v[120:123]
	v_mfma_f32_16x16x32_bf16 v[108:111], v[132:135], v[204:207], v[108:111]
	v_mfma_f32_16x16x32_bf16 v[104:107], v[158:161], v[204:207], v[104:107]
	v_mfma_f32_16x16x32_bf16 v[92:95], v[132:135], v[214:217], v[92:95]
	v_mfma_f32_16x16x32_bf16 v[88:91], v[158:161], v[214:217], v[88:91]
	v_mfma_f32_16x16x32_bf16 v[76:79], v[132:135], v[222:225], v[76:79]
	v_mfma_f32_16x16x32_bf16 v[72:75], v[158:161], v[222:225], v[72:75]
	v_mfma_f32_16x16x32_bf16 v[116:119], v[172:175], v[192:195], v[116:119]
	v_mfma_f32_16x16x32_bf16 v[112:115], v[184:187], v[192:195], v[112:115]
	v_mfma_f32_16x16x32_bf16 v[100:103], v[172:175], v[200:203], v[100:103]
	v_mfma_f32_16x16x32_bf16 v[96:99], v[184:187], v[200:203], v[96:99]
	v_mfma_f32_16x16x32_bf16 v[84:87], v[172:175], v[210:213], v[84:87]
	v_mfma_f32_16x16x32_bf16 v[80:83], v[184:187], v[210:213], v[80:83]
	v_mfma_f32_16x16x32_bf16 v[68:71], v[172:175], v[218:221], v[68:71]
	v_mfma_f32_16x16x32_bf16 v[64:67], v[184:187], v[218:221], v[64:67]
	v_mfma_f32_16x16x32_bf16 v[116:119], v[180:183], v[196:199], v[116:119]
	v_mfma_f32_16x16x32_bf16 v[112:115], v[188:191], v[196:199], v[112:115]
	v_mfma_f32_16x16x32_bf16 v[100:103], v[180:183], v[204:207], v[100:103]
	v_mfma_f32_16x16x32_bf16 v[96:99], v[188:191], v[204:207], v[96:99]
	v_mfma_f32_16x16x32_bf16 v[84:87], v[180:183], v[214:217], v[84:87]
	v_mfma_f32_16x16x32_bf16 v[80:83], v[188:191], v[214:217], v[80:83]
	v_mfma_f32_16x16x32_bf16 v[68:71], v[180:183], v[222:225], v[68:71]
	v_mfma_f32_16x16x32_bf16 v[64:67], v[188:191], v[222:225], v[64:67]
	s_setprio 0
	s_barrier
	s_add_i32 s34, s58, s37
	v_lshl_add_u64 v[162:163], v[162:163], 0, s[12:13]
	s_mov_b32 m0, s34
	ds_read_b128 v[192:195], v171 offset:49152
	ds_read_b128 v[196:199], v171 offset:50176
	ds_read_b128 v[200:203], v171 offset:51200
	ds_read_b128 v[204:207], v171 offset:52224
	ds_read_b128 v[210:213], v171 offset:53248
	ds_read_b128 v[214:217], v171 offset:54272
	ds_read_b128 v[218:221], v171 offset:55296
	ds_read_b128 v[222:225], v171 offset:56320
	global_load_lds_dwordx4 v[162:163], off
	s_add_i32 m0, s34, 0x2000
	s_add_u32 s30, s30, 0x80080
	v_lshl_add_u64 v[162:163], v[176:177], 0, s[12:13]
	s_addc_u32 s31, s31, 0
	s_add_i32 s34, s59, s37
	global_load_lds_dwordx4 v[162:163], off
	v_lshl_add_u64 v[162:163], s[30:31], 0, v[140:141]
	s_mov_b32 m0, s34
	s_nop 0
	global_load_lds_dwordx4 v[162:163], off
	v_lshl_add_u64 v[162:163], s[30:31], 0, v[144:145]
	s_add_i32 m0, s34, 0x2000
	s_nop 0
	global_load_lds_dwordx4 v[162:163], off
	v_lshl_add_u64 v[162:163], v[226:227], 0, s[12:13]
	s_mov_b32 m0, s43
	s_nop 0
	global_load_lds_dwordx4 v[162:163], off
	v_lshl_add_u64 v[162:163], v[228:229], 0, s[12:13]
	s_mov_b32 m0, s44
	s_nop 0
	global_load_lds_dwordx4 v[162:163], off
	s_waitcnt vmcnt(8)
	s_waitcnt lgkmcnt(0)
	s_barrier
	s_setprio 1
	v_mfma_f32_16x16x32_bf16 v[60:63], v[128:131], v[192:195], v[60:63]
	v_mfma_f32_16x16x32_bf16 v[56:59], v[154:157], v[192:195], v[56:59]
	v_mfma_f32_16x16x32_bf16 v[44:47], v[128:131], v[200:203], v[44:47]
	v_mfma_f32_16x16x32_bf16 v[40:43], v[154:157], v[200:203], v[40:43]
	v_mfma_f32_16x16x32_bf16 v[28:31], v[128:131], v[210:213], v[28:31]
	v_mfma_f32_16x16x32_bf16 v[24:27], v[154:157], v[210:213], v[24:27]
	v_mfma_f32_16x16x32_bf16 v[12:15], v[128:131], v[218:221], v[12:15]
	v_mfma_f32_16x16x32_bf16 v[8:11], v[154:157], v[218:221], v[8:11]
	v_mfma_f32_16x16x32_bf16 v[60:63], v[132:135], v[196:199], v[60:63]
	v_mfma_f32_16x16x32_bf16 v[56:59], v[158:161], v[196:199], v[56:59]
	v_mfma_f32_16x16x32_bf16 v[44:47], v[132:135], v[204:207], v[44:47]
	v_mfma_f32_16x16x32_bf16 v[40:43], v[158:161], v[204:207], v[40:43]
	v_mfma_f32_16x16x32_bf16 v[28:31], v[132:135], v[214:217], v[28:31]
	v_mfma_f32_16x16x32_bf16 v[24:27], v[158:161], v[214:217], v[24:27]
	v_mfma_f32_16x16x32_bf16 v[12:15], v[132:135], v[222:225], v[12:15]
	v_mfma_f32_16x16x32_bf16 v[8:11], v[158:161], v[222:225], v[8:11]
	v_mfma_f32_16x16x32_bf16 v[52:55], v[172:175], v[192:195], v[52:55]
	v_mfma_f32_16x16x32_bf16 v[48:51], v[184:187], v[192:195], v[48:51]
	v_mfma_f32_16x16x32_bf16 v[36:39], v[172:175], v[200:203], v[36:39]
	v_mfma_f32_16x16x32_bf16 v[32:35], v[184:187], v[200:203], v[32:35]
	v_mfma_f32_16x16x32_bf16 v[20:23], v[172:175], v[210:213], v[20:23]
	v_mfma_f32_16x16x32_bf16 v[16:19], v[184:187], v[210:213], v[16:19]
	v_mfma_f32_16x16x32_bf16 v[4:7], v[172:175], v[218:221], v[4:7]
	v_mfma_f32_16x16x32_bf16 v[0:3], v[184:187], v[218:221], v[0:3]
	v_mfma_f32_16x16x32_bf16 v[52:55], v[180:183], v[196:199], v[52:55]
	v_mfma_f32_16x16x32_bf16 v[48:51], v[188:191], v[196:199], v[48:51]
	v_mfma_f32_16x16x32_bf16 v[36:39], v[180:183], v[204:207], v[36:39]
	v_mfma_f32_16x16x32_bf16 v[32:35], v[188:191], v[204:207], v[32:35]
	v_mfma_f32_16x16x32_bf16 v[20:23], v[180:183], v[214:217], v[20:23]
	v_mfma_f32_16x16x32_bf16 v[16:19], v[188:191], v[214:217], v[16:19]
	v_mfma_f32_16x16x32_bf16 v[4:7], v[180:183], v[222:225], v[4:7]
	v_mfma_f32_16x16x32_bf16 v[0:3], v[188:191], v[222:225], v[0:3]
	s_setprio 0
	s_barrier
	s_add_i32 s57, s57, 2
	s_add_u32 s28, s28, 0x100
	s_addc_u32 s29, s29, 0
	s_add_u32 s25, s25, 0x100
	s_addc_u32 s27, s27, 0
	s_cmp_gt_u32 s57, 29
	s_cbranch_scc0 .LBB0_965
	s_and_b64 vcc, exec, s[14:15]
	s_cbranch_vccz .LBB0_968
	s_barrier

.LBB0_1082:
	s_add_u32 s23, s30, s21
	s_addc_u32 s25, s31, 0
	s_add_u32 s37, s23, 0x100
	s_addc_u32 s44, s25, 0
	s_and_b64 s[42:43], s[40:41], exec
	s_cselect_b32 s45, s29, s44
	s_cselect_b32 s44, s28, s37
	s_add_u32 s21, s26, s21
	s_addc_u32 s37, s27, 0
	s_add_u32 s21, s21, 0x100
	s_addc_u32 s37, s37, 0
	s_and_b64 s[40:41], s[40:41], exec
	s_cselect_b32 s47, s35, s37
	s_cselect_b32 s46, s34, s21
	s_add_u32 s50, s23, 0x80080
	s_addc_u32 s51, s25, 0
	s_add_i32 s76, s62, s2
	ds_read_b128 v[146:149], v131
	ds_read_b128 v[150:153], v131 offset:1024
	ds_read_b128 v[154:157], v131 offset:2048
	ds_read_b128 v[158:161], v131 offset:3072
	ds_read_b128 v[166:169], v132
	ds_read_b128 v[170:173], v132 offset:1024
	ds_read_b128 v[174:177], v132 offset:2048
	ds_read_b128 v[180:183], v132 offset:3072
	s_add_i32 m0, s3, 0xc000
	s_add_i32 s77, s3, 0xe000
	s_add_i32 s73, s76, 0x2000
	s_add_u32 s48, s46, 0x80000
	s_addc_u32 s49, s47, 0
	s_add_i32 s75, s63, s2
	s_add_i32 s74, s75, 0x2000
	s_add_i32 s72, 0, 0x18000
	s_add_i32 s71, 0, 0x1c000
	s_add_u32 s42, s44, 0x80000
	s_addc_u32 s43, s45, 0
	s_add_i32 s37, s72, s2
	s_add_i32 s23, s37, 0x2000
	s_add_u32 s40, s46, 0x80080
	s_addc_u32 s41, s47, 0
	s_add_i32 s25, s71, s2
	s_add_i32 s21, s25, 0x2000
	v_lshl_add_u64 v[134:135], s[50:51], 0, v[138:139]
	ds_read_b128 v[184:187], v133
	ds_read_b128 v[188:191], v133 offset:1024
	ds_read_b128 v[192:195], v133 offset:2048
	ds_read_b128 v[196:199], v133 offset:3072
	ds_read_b128 v[200:203], v133 offset:4096
	ds_read_b128 v[204:207], v133 offset:5120
	ds_read_b128 v[210:213], v133 offset:6144
	ds_read_b128 v[214:217], v133 offset:7168
	global_load_lds_dwordx4 v[134:135], off
	v_lshl_add_u64 v[134:135], s[50:51], 0, v[142:143]
	s_mov_b32 m0, s77
	s_nop 0
	global_load_lds_dwordx4 v[134:135], off
	s_waitcnt vmcnt(8)
	s_waitcnt lgkmcnt(0)
	s_barrier
	s_setprio 1
	v_mfma_f32_16x16x32_bf16 v[124:127], v[146:149], v[184:187], v[124:127]
	v_mfma_f32_16x16x32_bf16 v[120:123], v[154:157], v[184:187], v[120:123]
	v_mfma_f32_16x16x32_bf16 v[116:119], v[146:149], v[192:195], v[116:119]
	v_mfma_f32_16x16x32_bf16 v[112:115], v[154:157], v[192:195], v[112:115]
	v_mfma_f32_16x16x32_bf16 v[108:111], v[146:149], v[200:203], v[108:111]
	v_mfma_f32_16x16x32_bf16 v[104:107], v[154:157], v[200:203], v[104:107]
	v_mfma_f32_16x16x32_bf16 v[100:103], v[146:149], v[210:213], v[100:103]
	v_mfma_f32_16x16x32_bf16 v[96:99], v[154:157], v[210:213], v[96:99]
	v_mfma_f32_16x16x32_bf16 v[124:127], v[150:153], v[188:191], v[124:127]
	v_mfma_f32_16x16x32_bf16 v[120:123], v[158:161], v[188:191], v[120:123]
	v_mfma_f32_16x16x32_bf16 v[116:119], v[150:153], v[196:199], v[116:119]
	v_mfma_f32_16x16x32_bf16 v[112:115], v[158:161], v[196:199], v[112:115]
	v_mfma_f32_16x16x32_bf16 v[108:111], v[150:153], v[204:207], v[108:111]
	v_mfma_f32_16x16x32_bf16 v[104:107], v[158:161], v[204:207], v[104:107]
	v_mfma_f32_16x16x32_bf16 v[100:103], v[150:153], v[214:217], v[100:103]
	v_mfma_f32_16x16x32_bf16 v[96:99], v[158:161], v[214:217], v[96:99]
	v_mfma_f32_16x16x32_bf16 v[92:95], v[166:169], v[184:187], v[92:95]
	v_mfma_f32_16x16x32_bf16 v[88:91], v[174:177], v[184:187], v[88:91]
	v_mfma_f32_16x16x32_bf16 v[84:87], v[166:169], v[192:195], v[84:87]
	v_mfma_f32_16x16x32_bf16 v[80:83], v[174:177], v[192:195], v[80:83]
	v_mfma_f32_16x16x32_bf16 v[76:79], v[166:169], v[200:203], v[76:79]
	v_mfma_f32_16x16x32_bf16 v[72:75], v[174:177], v[200:203], v[72:75]
	v_mfma_f32_16x16x32_bf16 v[68:71], v[166:169], v[210:213], v[68:71]
	v_mfma_f32_16x16x32_bf16 v[64:67], v[174:177], v[210:213], v[64:67]
	v_mfma_f32_16x16x32_bf16 v[92:95], v[170:173], v[188:191], v[92:95]
	v_mfma_f32_16x16x32_bf16 v[88:91], v[180:183], v[188:191], v[88:91]
	v_mfma_f32_16x16x32_bf16 v[84:87], v[170:173], v[196:199], v[84:87]
	v_mfma_f32_16x16x32_bf16 v[80:83], v[180:183], v[196:199], v[80:83]
	v_mfma_f32_16x16x32_bf16 v[76:79], v[170:173], v[204:207], v[76:79]
	v_mfma_f32_16x16x32_bf16 v[72:75], v[180:183], v[204:207], v[72:75]
	v_mfma_f32_16x16x32_bf16 v[68:71], v[170:173], v[214:217], v[68:71]
	v_mfma_f32_16x16x32_bf16 v[64:67], v[180:183], v[214:217], v[64:67]
	s_setprio 0
	s_barrier
	s_mov_b32 m0, s76
	v_lshl_add_u64 v[134:135], s[46:47], 0, v[140:141]
	ds_read_b128 v[184:187], v133 offset:16384
	ds_read_b128 v[188:191], v133 offset:17408
	ds_read_b128 v[192:195], v133 offset:18432
	ds_read_b128 v[196:199], v133 offset:19456
	ds_read_b128 v[200:203], v133 offset:20480
	ds_read_b128 v[204:207], v133 offset:21504
	ds_read_b128 v[210:213], v133 offset:22528
	ds_read_b128 v[214:217], v133 offset:23552
	global_load_lds_dwordx4 v[134:135], off
	v_lshl_add_u64 v[162:163], s[46:47], 0, v[144:145]
	s_mov_b32 m0, s73
	v_lshl_add_u64 v[218:219], s[48:49], 0, v[140:141]
	global_load_lds_dwordx4 v[162:163], off
	s_mov_b32 m0, s75
	v_lshl_add_u64 v[220:221], s[44:45], 0, v[142:143]
	global_load_lds_dwordx4 v[218:219], off
	v_lshl_add_u64 v[218:219], s[48:49], 0, v[144:145]
	s_mov_b32 m0, s74
	s_nop 0
	global_load_lds_dwordx4 v[218:219], off
	v_lshl_add_u64 v[218:219], s[44:45], 0, v[138:139]
	s_mov_b32 m0, s3
	s_nop 0
	global_load_lds_dwordx4 v[218:219], off
	s_mov_b32 m0, s56
	s_nop 0
	global_load_lds_dwordx4 v[220:221], off
	s_waitcnt vmcnt(8)
	s_waitcnt lgkmcnt(0)
	s_barrier
	s_setprio 1
	v_mfma_f32_16x16x32_bf16 v[60:63], v[146:149], v[184:187], v[60:63]
	v_mfma_f32_16x16x32_bf16 v[56:59], v[154:157], v[184:187], v[56:59]
	v_mfma_f32_16x16x32_bf16 v[52:55], v[146:149], v[192:195], v[52:55]
	v_mfma_f32_16x16x32_bf16 v[48:51], v[154:157], v[192:195], v[48:51]
	v_mfma_f32_16x16x32_bf16 v[44:47], v[146:149], v[200:203], v[44:47]
	v_mfma_f32_16x16x32_bf16 v[40:43], v[154:157], v[200:203], v[40:43]
	v_mfma_f32_16x16x32_bf16 v[36:39], v[146:149], v[210:213], v[36:39]
	v_mfma_f32_16x16x32_bf16 v[32:35], v[154:157], v[210:213], v[32:35]
	v_mfma_f32_16x16x32_bf16 v[60:63], v[150:153], v[188:191], v[60:63]
	v_mfma_f32_16x16x32_bf16 v[56:59], v[158:161], v[188:191], v[56:59]
	v_mfma_f32_16x16x32_bf16 v[52:55], v[150:153], v[196:199], v[52:55]
	v_mfma_f32_16x16x32_bf16 v[48:51], v[158:161], v[196:199], v[48:51]
	v_mfma_f32_16x16x32_bf16 v[44:47], v[150:153], v[204:207], v[44:47]
	v_mfma_f32_16x16x32_bf16 v[40:43], v[158:161], v[204:207], v[40:43]
	v_mfma_f32_16x16x32_bf16 v[36:39], v[150:153], v[214:217], v[36:39]
	v_mfma_f32_16x16x32_bf16 v[32:35], v[158:161], v[214:217], v[32:35]
	v_mfma_f32_16x16x32_bf16 v[28:31], v[166:169], v[184:187], v[28:31]
	v_mfma_f32_16x16x32_bf16 v[24:27], v[174:177], v[184:187], v[24:27]
	v_mfma_f32_16x16x32_bf16 v[20:23], v[166:169], v[192:195], v[20:23]
	v_mfma_f32_16x16x32_bf16 v[16:19], v[174:177], v[192:195], v[16:19]
	v_mfma_f32_16x16x32_bf16 v[12:15], v[166:169], v[200:203], v[12:15]
	v_mfma_f32_16x16x32_bf16 v[8:11], v[174:177], v[200:203], v[8:11]
	v_mfma_f32_16x16x32_bf16 v[4:7], v[166:169], v[210:213], v[4:7]
	v_mfma_f32_16x16x32_bf16 v[0:3], v[174:177], v[210:213], v[0:3]
	v_mfma_f32_16x16x32_bf16 v[28:31], v[170:173], v[188:191], v[28:31]
	v_mfma_f32_16x16x32_bf16 v[24:27], v[180:183], v[188:191], v[24:27]
	v_mfma_f32_16x16x32_bf16 v[20:23], v[170:173], v[196:199], v[20:23]
	v_mfma_f32_16x16x32_bf16 v[16:19], v[180:183], v[196:199], v[16:19]
	v_mfma_f32_16x16x32_bf16 v[12:15], v[170:173], v[204:207], v[12:15]
	v_mfma_f32_16x16x32_bf16 v[8:11], v[180:183], v[204:207], v[8:11]
	v_mfma_f32_16x16x32_bf16 v[4:7], v[170:173], v[214:217], v[4:7]
	v_mfma_f32_16x16x32_bf16 v[0:3], v[180:183], v[214:217], v[0:3]
	s_setprio 0
	s_barrier
	v_add_u32_e32 v137, s72, v130
	ds_read_b128 v[146:149], v137
	ds_read_b128 v[150:153], v137 offset:1024
	ds_read_b128 v[154:157], v137 offset:2048
	ds_read_b128 v[158:161], v137 offset:3072
	v_add_u32_e32 v137, s71, v130
	ds_read_b128 v[166:169], v137
	ds_read_b128 v[170:173], v137 offset:1024
	ds_read_b128 v[174:177], v137 offset:2048
	ds_read_b128 v[180:183], v137 offset:3072
	s_mov_b32 m0, s57
	v_lshl_add_u64 v[222:223], s[42:43], 0, v[138:139]
	ds_read_b128 v[184:187], v133 offset:32768
	ds_read_b128 v[188:191], v133 offset:33792
	ds_read_b128 v[192:195], v133 offset:34816
	ds_read_b128 v[196:199], v133 offset:35840
	ds_read_b128 v[200:203], v133 offset:36864
	ds_read_b128 v[204:207], v133 offset:37888
	ds_read_b128 v[210:213], v133 offset:38912
	ds_read_b128 v[214:217], v133 offset:39936
	global_load_lds_dwordx4 v[222:223], off
	v_lshl_add_u64 v[222:223], s[42:43], 0, v[142:143]
	s_mov_b32 m0, s58
	s_nop 0
	global_load_lds_dwordx4 v[222:223], off
	s_waitcnt vmcnt(8)
	s_waitcnt lgkmcnt(0)
	s_barrier
	s_setprio 1
	v_mfma_f32_16x16x32_bf16 v[124:127], v[146:149], v[184:187], v[124:127]
	v_mfma_f32_16x16x32_bf16 v[120:123], v[154:157], v[184:187], v[120:123]
	v_mfma_f32_16x16x32_bf16 v[116:119], v[146:149], v[192:195], v[116:119]
	v_mfma_f32_16x16x32_bf16 v[112:115], v[154:157], v[192:195], v[112:115]
	v_mfma_f32_16x16x32_bf16 v[108:111], v[146:149], v[200:203], v[108:111]
	v_mfma_f32_16x16x32_bf16 v[104:107], v[154:157], v[200:203], v[104:107]
	v_mfma_f32_16x16x32_bf16 v[100:103], v[146:149], v[210:213], v[100:103]
	v_mfma_f32_16x16x32_bf16 v[96:99], v[154:157], v[210:213], v[96:99]
	v_mfma_f32_16x16x32_bf16 v[124:127], v[150:153], v[188:191], v[124:127]
	v_mfma_f32_16x16x32_bf16 v[120:123], v[158:161], v[188:191], v[120:123]
	v_mfma_f32_16x16x32_bf16 v[116:119], v[150:153], v[196:199], v[116:119]
	v_mfma_f32_16x16x32_bf16 v[112:115], v[158:161], v[196:199], v[112:115]
	v_mfma_f32_16x16x32_bf16 v[108:111], v[150:153], v[204:207], v[108:111]
	v_mfma_f32_16x16x32_bf16 v[104:107], v[158:161], v[204:207], v[104:107]
	v_mfma_f32_16x16x32_bf16 v[100:103], v[150:153], v[214:217], v[100:103]
	v_mfma_f32_16x16x32_bf16 v[96:99], v[158:161], v[214:217], v[96:99]
	v_mfma_f32_16x16x32_bf16 v[92:95], v[166:169], v[184:187], v[92:95]
	v_mfma_f32_16x16x32_bf16 v[88:91], v[174:177], v[184:187], v[88:91]
	v_mfma_f32_16x16x32_bf16 v[84:87], v[166:169], v[192:195], v[84:87]
	v_mfma_f32_16x16x32_bf16 v[80:83], v[174:177], v[192:195], v[80:83]
	v_mfma_f32_16x16x32_bf16 v[76:79], v[166:169], v[200:203], v[76:79]
	v_mfma_f32_16x16x32_bf16 v[72:75], v[174:177], v[200:203], v[72:75]
	v_mfma_f32_16x16x32_bf16 v[68:71], v[166:169], v[210:213], v[68:71]
	v_mfma_f32_16x16x32_bf16 v[64:67], v[174:177], v[210:213], v[64:67]
	v_mfma_f32_16x16x32_bf16 v[92:95], v[170:173], v[188:191], v[92:95]
	v_mfma_f32_16x16x32_bf16 v[88:91], v[180:183], v[188:191], v[88:91]
	v_mfma_f32_16x16x32_bf16 v[84:87], v[170:173], v[196:199], v[84:87]
	v_mfma_f32_16x16x32_bf16 v[80:83], v[180:183], v[196:199], v[80:83]
	v_mfma_f32_16x16x32_bf16 v[76:79], v[170:173], v[204:207], v[76:79]
	v_mfma_f32_16x16x32_bf16 v[72:75], v[180:183], v[204:207], v[72:75]
	v_mfma_f32_16x16x32_bf16 v[68:71], v[170:173], v[214:217], v[68:71]
	v_mfma_f32_16x16x32_bf16 v[64:67], v[180:183], v[214:217], v[64:67]
	s_setprio 0
	s_barrier
	s_mov_b32 m0, s37
	v_lshl_add_u64 v[134:135], v[134:135], 0, s[16:17]
	ds_read_b128 v[184:187], v133 offset:49152
	ds_read_b128 v[188:191], v133 offset:50176
	ds_read_b128 v[192:195], v133 offset:51200
	ds_read_b128 v[196:199], v133 offset:52224
	ds_read_b128 v[200:203], v133 offset:53248
	ds_read_b128 v[204:207], v133 offset:54272
	ds_read_b128 v[210:213], v133 offset:55296
	ds_read_b128 v[214:217], v133 offset:56320
	global_load_lds_dwordx4 v[134:135], off
	v_lshl_add_u64 v[134:135], v[162:163], 0, s[16:17]
	s_mov_b32 m0, s23
	s_nop 0
	global_load_lds_dwordx4 v[134:135], off
	v_lshl_add_u64 v[134:135], s[40:41], 0, v[140:141]
	s_mov_b32 m0, s25
	s_nop 0
	global_load_lds_dwordx4 v[134:135], off
	v_lshl_add_u64 v[134:135], s[40:41], 0, v[144:145]
	s_mov_b32 m0, s21
	s_nop 0
	global_load_lds_dwordx4 v[134:135], off
	v_lshl_add_u64 v[134:135], v[218:219], 0, s[16:17]
	s_mov_b32 m0, s60
	s_nop 0
	global_load_lds_dwordx4 v[134:135], off
	v_lshl_add_u64 v[134:135], v[220:221], 0, s[16:17]
	s_mov_b32 m0, s61
	s_nop 0
	global_load_lds_dwordx4 v[134:135], off
	s_waitcnt vmcnt(8)
	s_waitcnt lgkmcnt(0)
	s_barrier
	s_setprio 1
	v_mfma_f32_16x16x32_bf16 v[60:63], v[146:149], v[184:187], v[60:63]
	v_mfma_f32_16x16x32_bf16 v[56:59], v[154:157], v[184:187], v[56:59]
	v_mfma_f32_16x16x32_bf16 v[52:55], v[146:149], v[192:195], v[52:55]
	v_mfma_f32_16x16x32_bf16 v[48:51], v[154:157], v[192:195], v[48:51]
	v_mfma_f32_16x16x32_bf16 v[44:47], v[146:149], v[200:203], v[44:47]
	v_mfma_f32_16x16x32_bf16 v[40:43], v[154:157], v[200:203], v[40:43]
	v_mfma_f32_16x16x32_bf16 v[36:39], v[146:149], v[210:213], v[36:39]
	v_mfma_f32_16x16x32_bf16 v[32:35], v[154:157], v[210:213], v[32:35]
	v_mfma_f32_16x16x32_bf16 v[60:63], v[150:153], v[188:191], v[60:63]
	v_mfma_f32_16x16x32_bf16 v[56:59], v[158:161], v[188:191], v[56:59]
	v_mfma_f32_16x16x32_bf16 v[52:55], v[150:153], v[196:199], v[52:55]
	v_mfma_f32_16x16x32_bf16 v[48:51], v[158:161], v[196:199], v[48:51]
	v_mfma_f32_16x16x32_bf16 v[44:47], v[150:153], v[204:207], v[44:47]
	v_mfma_f32_16x16x32_bf16 v[40:43], v[158:161], v[204:207], v[40:43]
	v_mfma_f32_16x16x32_bf16 v[36:39], v[150:153], v[214:217], v[36:39]
	v_mfma_f32_16x16x32_bf16 v[32:35], v[158:161], v[214:217], v[32:35]
	v_mfma_f32_16x16x32_bf16 v[28:31], v[166:169], v[184:187], v[28:31]
	v_mfma_f32_16x16x32_bf16 v[24:27], v[174:177], v[184:187], v[24:27]
	v_mfma_f32_16x16x32_bf16 v[20:23], v[166:169], v[192:195], v[20:23]
	v_mfma_f32_16x16x32_bf16 v[16:19], v[174:177], v[192:195], v[16:19]
	v_mfma_f32_16x16x32_bf16 v[12:15], v[166:169], v[200:203], v[12:15]
	v_mfma_f32_16x16x32_bf16 v[8:11], v[174:177], v[200:203], v[8:11]
	v_mfma_f32_16x16x32_bf16 v[4:7], v[166:169], v[210:213], v[4:7]
	v_mfma_f32_16x16x32_bf16 v[0:3], v[174:177], v[210:213], v[0:3]
	v_mfma_f32_16x16x32_bf16 v[28:31], v[170:173], v[188:191], v[28:31]
	v_mfma_f32_16x16x32_bf16 v[24:27], v[180:183], v[188:191], v[24:27]
	v_mfma_f32_16x16x32_bf16 v[20:23], v[170:173], v[196:199], v[20:23]
	v_mfma_f32_16x16x32_bf16 v[16:19], v[180:183], v[196:199], v[16:19]
	v_mfma_f32_16x16x32_bf16 v[12:15], v[170:173], v[204:207], v[12:15]
	v_mfma_f32_16x16x32_bf16 v[8:11], v[180:183], v[204:207], v[8:11]
	v_mfma_f32_16x16x32_bf16 v[4:7], v[170:173], v[214:217], v[4:7]
	v_mfma_f32_16x16x32_bf16 v[0:3], v[180:183], v[214:217], v[0:3]
	s_setprio 0
	s_barrier
	s_movk_i32 s21, 0x100
	s_andn2_b64 vcc, exec, s[38:39]
	s_mov_b64 s[40:41], -1
	s_mov_b64 s[38:39], 0
	s_cbranch_vccz .LBB0_1082
	s_and_b64 vcc, exec, s[18:19]
	s_cbranch_vccz .LBB0_1085
	s_barrier

.LBB0_1298:
	ds_read_b128 v[162:165], v159
	ds_read_b128 v[166:169], v159 offset:1024
	ds_read_b128 v[170:173], v159 offset:2048
	ds_read_b128 v[174:177], v159 offset:3072
	ds_read_b128 v[180:183], v160
	ds_read_b128 v[184:187], v160 offset:1024
	ds_read_b128 v[188:191], v160 offset:2048
	ds_read_b128 v[192:195], v160 offset:3072
	s_add_u32 s28, s26, 0xfff80080
	s_addc_u32 s29, s27, -1
	s_cmp_eq_u32 s49, 28
	s_cselect_b32 s31, s3, s29
	s_cselect_b32 s30, s19, s28
	s_cselect_b32 s29, s17, s48
	s_cselect_b32 s28, s46, s47
	v_lshl_add_u64 v[230:231], s[26:27], 0, v[138:139]
	s_add_i32 m0, s25, 0xc000
	ds_read_b128 v[196:199], v161
	ds_read_b128 v[200:203], v161 offset:1024
	ds_read_b128 v[204:207], v161 offset:2048
	ds_read_b128 v[210:213], v161 offset:3072
	ds_read_b128 v[214:217], v161 offset:4096
	ds_read_b128 v[218:221], v161 offset:5120
	ds_read_b128 v[222:225], v161 offset:6144
	ds_read_b128 v[226:229], v161 offset:7168
	global_load_lds_dwordx4 v[230:231], off
	v_lshl_add_u64 v[230:231], s[26:27], 0, v[140:141]
	s_add_i32 m0, s25, 0xe000
	s_nop 0
	global_load_lds_dwordx4 v[230:231], off
	s_waitcnt vmcnt(8)
	s_waitcnt lgkmcnt(0)
	s_barrier
	s_setprio 1
	v_mfma_f32_16x16x32_bf16 v[124:127], v[162:165], v[196:199], v[124:127]
	v_mfma_f32_16x16x32_bf16 v[116:119], v[170:173], v[196:199], v[116:119]
	v_mfma_f32_16x16x32_bf16 v[108:111], v[162:165], v[204:207], v[108:111]
	v_mfma_f32_16x16x32_bf16 v[100:103], v[170:173], v[204:207], v[100:103]
	v_mfma_f32_16x16x32_bf16 v[92:95], v[162:165], v[214:217], v[92:95]
	v_mfma_f32_16x16x32_bf16 v[84:87], v[170:173], v[214:217], v[84:87]
	v_mfma_f32_16x16x32_bf16 v[76:79], v[162:165], v[222:225], v[76:79]
	v_mfma_f32_16x16x32_bf16 v[68:71], v[170:173], v[222:225], v[68:71]
	v_mfma_f32_16x16x32_bf16 v[124:127], v[166:169], v[200:203], v[124:127]
	v_mfma_f32_16x16x32_bf16 v[116:119], v[174:177], v[200:203], v[116:119]
	v_mfma_f32_16x16x32_bf16 v[108:111], v[166:169], v[210:213], v[108:111]
	v_mfma_f32_16x16x32_bf16 v[100:103], v[174:177], v[210:213], v[100:103]
	v_mfma_f32_16x16x32_bf16 v[92:95], v[166:169], v[218:221], v[92:95]
	v_mfma_f32_16x16x32_bf16 v[84:87], v[174:177], v[218:221], v[84:87]
	v_mfma_f32_16x16x32_bf16 v[76:79], v[166:169], v[226:229], v[76:79]
	v_mfma_f32_16x16x32_bf16 v[68:71], v[174:177], v[226:229], v[68:71]
	v_mfma_f32_16x16x32_bf16 v[120:123], v[180:183], v[196:199], v[120:123]
	v_mfma_f32_16x16x32_bf16 v[112:115], v[188:191], v[196:199], v[112:115]
	v_mfma_f32_16x16x32_bf16 v[104:107], v[180:183], v[204:207], v[104:107]
	v_mfma_f32_16x16x32_bf16 v[96:99], v[188:191], v[204:207], v[96:99]
	v_mfma_f32_16x16x32_bf16 v[88:91], v[180:183], v[214:217], v[88:91]
	v_mfma_f32_16x16x32_bf16 v[80:83], v[188:191], v[214:217], v[80:83]
	v_mfma_f32_16x16x32_bf16 v[72:75], v[180:183], v[222:225], v[72:75]
	v_mfma_f32_16x16x32_bf16 v[64:67], v[188:191], v[222:225], v[64:67]
	v_mfma_f32_16x16x32_bf16 v[120:123], v[184:187], v[200:203], v[120:123]
	v_mfma_f32_16x16x32_bf16 v[112:115], v[192:195], v[200:203], v[112:115]
	v_mfma_f32_16x16x32_bf16 v[104:107], v[184:187], v[210:213], v[104:107]
	v_mfma_f32_16x16x32_bf16 v[96:99], v[192:195], v[210:213], v[96:99]
	v_mfma_f32_16x16x32_bf16 v[88:91], v[184:187], v[218:221], v[88:91]
	v_mfma_f32_16x16x32_bf16 v[80:83], v[192:195], v[218:221], v[80:83]
	v_mfma_f32_16x16x32_bf16 v[72:75], v[184:187], v[226:229], v[72:75]
	v_mfma_f32_16x16x32_bf16 v[64:67], v[192:195], v[226:229], v[64:67]
	s_setprio 0
	s_barrier
	s_add_i32 s50, s43, s36
	v_lshl_add_u64 v[230:231], s[28:29], 0, v[132:133]
	s_mov_b32 m0, s50
	ds_read_b128 v[196:199], v161 offset:16384
	ds_read_b128 v[200:203], v161 offset:17408
	ds_read_b128 v[204:207], v161 offset:18432
	ds_read_b128 v[210:213], v161 offset:19456
	ds_read_b128 v[214:217], v161 offset:20480
	ds_read_b128 v[218:221], v161 offset:21504
	ds_read_b128 v[222:225], v161 offset:22528
	ds_read_b128 v[226:229], v161 offset:23552
	global_load_lds_dwordx4 v[230:231], off
	s_add_i32 m0, s50, 0x2000
	s_add_u32 s50, s28, 0x80000
	v_lshl_add_u64 v[232:233], s[28:29], 0, v[136:137]
	s_addc_u32 s51, s29, 0
	s_add_i32 s56, s44, s36
	global_load_lds_dwordx4 v[232:233], off
	v_lshl_add_u64 v[234:235], s[50:51], 0, v[132:133]
	s_mov_b32 m0, s56
	v_lshl_add_u64 v[236:237], s[30:31], 0, v[134:135]
	global_load_lds_dwordx4 v[234:235], off
	v_lshl_add_u64 v[234:235], s[50:51], 0, v[136:137]
	s_add_i32 m0, s56, 0x2000
	s_nop 0
	global_load_lds_dwordx4 v[234:235], off
	v_lshl_add_u64 v[234:235], s[30:31], 0, v[130:131]
	s_mov_b32 m0, s25
	s_nop 0
	global_load_lds_dwordx4 v[234:235], off
	s_mov_b32 m0, s37
	s_nop 0
	global_load_lds_dwordx4 v[236:237], off
	s_waitcnt vmcnt(8)
	s_waitcnt lgkmcnt(0)
	s_barrier
	s_setprio 1
	v_mfma_f32_16x16x32_bf16 v[60:63], v[162:165], v[196:199], v[60:63]
	v_mfma_f32_16x16x32_bf16 v[52:55], v[170:173], v[196:199], v[52:55]
	v_mfma_f32_16x16x32_bf16 v[44:47], v[162:165], v[204:207], v[44:47]
	v_mfma_f32_16x16x32_bf16 v[36:39], v[170:173], v[204:207], v[36:39]
	v_mfma_f32_16x16x32_bf16 v[28:31], v[162:165], v[214:217], v[28:31]
	v_mfma_f32_16x16x32_bf16 v[20:23], v[170:173], v[214:217], v[20:23]
	v_mfma_f32_16x16x32_bf16 v[12:15], v[162:165], v[222:225], v[12:15]
	v_mfma_f32_16x16x32_bf16 v[4:7], v[170:173], v[222:225], v[4:7]
	v_mfma_f32_16x16x32_bf16 v[60:63], v[166:169], v[200:203], v[60:63]
	v_mfma_f32_16x16x32_bf16 v[52:55], v[174:177], v[200:203], v[52:55]
	v_mfma_f32_16x16x32_bf16 v[44:47], v[166:169], v[210:213], v[44:47]
	v_mfma_f32_16x16x32_bf16 v[36:39], v[174:177], v[210:213], v[36:39]
	v_mfma_f32_16x16x32_bf16 v[28:31], v[166:169], v[218:221], v[28:31]
	v_mfma_f32_16x16x32_bf16 v[20:23], v[174:177], v[218:221], v[20:23]
	v_mfma_f32_16x16x32_bf16 v[12:15], v[166:169], v[226:229], v[12:15]
	v_mfma_f32_16x16x32_bf16 v[4:7], v[174:177], v[226:229], v[4:7]
	v_mfma_f32_16x16x32_bf16 v[56:59], v[180:183], v[196:199], v[56:59]
	v_mfma_f32_16x16x32_bf16 v[48:51], v[188:191], v[196:199], v[48:51]
	v_mfma_f32_16x16x32_bf16 v[40:43], v[180:183], v[204:207], v[40:43]
	v_mfma_f32_16x16x32_bf16 v[32:35], v[188:191], v[204:207], v[32:35]
	v_mfma_f32_16x16x32_bf16 v[24:27], v[180:183], v[214:217], v[24:27]
	v_mfma_f32_16x16x32_bf16 v[16:19], v[188:191], v[214:217], v[16:19]
	v_mfma_f32_16x16x32_bf16 v[8:11], v[180:183], v[222:225], v[8:11]
	v_mfma_f32_16x16x32_bf16 v[0:3], v[188:191], v[222:225], v[0:3]
	v_mfma_f32_16x16x32_bf16 v[56:59], v[184:187], v[200:203], v[56:59]
	v_mfma_f32_16x16x32_bf16 v[48:51], v[192:195], v[200:203], v[48:51]
	v_mfma_f32_16x16x32_bf16 v[40:43], v[184:187], v[210:213], v[40:43]
	v_mfma_f32_16x16x32_bf16 v[32:35], v[192:195], v[210:213], v[32:35]
	v_mfma_f32_16x16x32_bf16 v[24:27], v[184:187], v[218:221], v[24:27]
	v_mfma_f32_16x16x32_bf16 v[16:19], v[192:195], v[218:221], v[16:19]
	v_mfma_f32_16x16x32_bf16 v[8:11], v[184:187], v[226:229], v[8:11]
	v_mfma_f32_16x16x32_bf16 v[0:3], v[192:195], v[226:229], v[0:3]
	s_setprio 0
	s_barrier
	s_add_i32 s50, 0, 0x18000
	s_add_i32 s51, 0, 0x1c000
	v_add_u32_e32 v174, s50, v157
	v_add_u32_e32 v178, s51, v157
	ds_read_b128 v[162:165], v174
	ds_read_b128 v[166:169], v174 offset:1024
	ds_read_b128 v[170:173], v174 offset:2048
	ds_read_b128 v[174:177], v174 offset:3072
	ds_read_b128 v[180:183], v178
	ds_read_b128 v[184:187], v178 offset:1024
	ds_read_b128 v[188:191], v178 offset:2048
	ds_read_b128 v[192:195], v178 offset:3072
	s_add_u32 s30, s30, 0x80000
	s_addc_u32 s31, s31, 0
	s_mov_b32 m0, s38
	v_lshl_add_u64 v[238:239], s[30:31], 0, v[130:131]
	ds_read_b128 v[196:199], v161 offset:32768
	ds_read_b128 v[200:203], v161 offset:33792
	ds_read_b128 v[204:207], v161 offset:34816
	ds_read_b128 v[210:213], v161 offset:35840
	ds_read_b128 v[214:217], v161 offset:36864
	ds_read_b128 v[218:221], v161 offset:37888
	ds_read_b128 v[222:225], v161 offset:38912
	ds_read_b128 v[226:229], v161 offset:39936
	global_load_lds_dwordx4 v[238:239], off
	v_lshl_add_u64 v[238:239], s[30:31], 0, v[134:135]
	s_mov_b32 m0, s39
	s_nop 0
	global_load_lds_dwordx4 v[238:239], off
	s_waitcnt vmcnt(8)
	s_waitcnt lgkmcnt(0)
	s_barrier
	s_setprio 1
	v_mfma_f32_16x16x32_bf16 v[124:127], v[162:165], v[196:199], v[124:127]
	v_mfma_f32_16x16x32_bf16 v[116:119], v[170:173], v[196:199], v[116:119]
	v_mfma_f32_16x16x32_bf16 v[108:111], v[162:165], v[204:207], v[108:111]
	v_mfma_f32_16x16x32_bf16 v[100:103], v[170:173], v[204:207], v[100:103]
	v_mfma_f32_16x16x32_bf16 v[92:95], v[162:165], v[214:217], v[92:95]
	v_mfma_f32_16x16x32_bf16 v[84:87], v[170:173], v[214:217], v[84:87]
	v_mfma_f32_16x16x32_bf16 v[76:79], v[162:165], v[222:225], v[76:79]
	v_mfma_f32_16x16x32_bf16 v[68:71], v[170:173], v[222:225], v[68:71]
	v_mfma_f32_16x16x32_bf16 v[124:127], v[166:169], v[200:203], v[124:127]
	v_mfma_f32_16x16x32_bf16 v[116:119], v[174:177], v[200:203], v[116:119]
	v_mfma_f32_16x16x32_bf16 v[108:111], v[166:169], v[210:213], v[108:111]
	v_mfma_f32_16x16x32_bf16 v[100:103], v[174:177], v[210:213], v[100:103]
	v_mfma_f32_16x16x32_bf16 v[92:95], v[166:169], v[218:221], v[92:95]
	v_mfma_f32_16x16x32_bf16 v[84:87], v[174:177], v[218:221], v[84:87]
	v_mfma_f32_16x16x32_bf16 v[76:79], v[166:169], v[226:229], v[76:79]
	v_mfma_f32_16x16x32_bf16 v[68:71], v[174:177], v[226:229], v[68:71]
	v_mfma_f32_16x16x32_bf16 v[120:123], v[180:183], v[196:199], v[120:123]
	v_mfma_f32_16x16x32_bf16 v[112:115], v[188:191], v[196:199], v[112:115]
	v_mfma_f32_16x16x32_bf16 v[104:107], v[180:183], v[204:207], v[104:107]
	v_mfma_f32_16x16x32_bf16 v[96:99], v[188:191], v[204:207], v[96:99]
	v_mfma_f32_16x16x32_bf16 v[88:91], v[180:183], v[214:217], v[88:91]
	v_mfma_f32_16x16x32_bf16 v[80:83], v[188:191], v[214:217], v[80:83]
	v_mfma_f32_16x16x32_bf16 v[72:75], v[180:183], v[222:225], v[72:75]
	v_mfma_f32_16x16x32_bf16 v[64:67], v[188:191], v[222:225], v[64:67]
	v_mfma_f32_16x16x32_bf16 v[120:123], v[184:187], v[200:203], v[120:123]
	v_mfma_f32_16x16x32_bf16 v[112:115], v[192:195], v[200:203], v[112:115]
	v_mfma_f32_16x16x32_bf16 v[104:107], v[184:187], v[210:213], v[104:107]
	v_mfma_f32_16x16x32_bf16 v[96:99], v[192:195], v[210:213], v[96:99]
	v_mfma_f32_16x16x32_bf16 v[88:91], v[184:187], v[218:221], v[88:91]
	v_mfma_f32_16x16x32_bf16 v[80:83], v[192:195], v[218:221], v[80:83]
	v_mfma_f32_16x16x32_bf16 v[72:75], v[184:187], v[226:229], v[72:75]
	v_mfma_f32_16x16x32_bf16 v[64:67], v[192:195], v[226:229], v[64:67]
	s_setprio 0
	s_barrier
	s_add_i32 s30, s50, s36
	v_lshl_add_u64 v[230:231], v[230:231], 0, s[12:13]
	s_mov_b32 m0, s30
	ds_read_b128 v[196:199], v161 offset:49152
	ds_read_b128 v[200:203], v161 offset:50176
	ds_read_b128 v[204:207], v161 offset:51200
	ds_read_b128 v[210:213], v161 offset:52224
	ds_read_b128 v[214:217], v161 offset:53248
	ds_read_b128 v[218:221], v161 offset:54272
	ds_read_b128 v[222:225], v161 offset:55296
	ds_read_b128 v[226:229], v161 offset:56320
	global_load_lds_dwordx4 v[230:231], off
	s_add_i32 m0, s30, 0x2000
	s_add_u32 s28, s28, 0x80080
	v_lshl_add_u64 v[230:231], v[232:233], 0, s[12:13]
	s_addc_u32 s29, s29, 0
	s_add_i32 s30, s51, s36
	global_load_lds_dwordx4 v[230:231], off
	v_lshl_add_u64 v[230:231], s[28:29], 0, v[132:133]
	s_mov_b32 m0, s30
	s_nop 0
	global_load_lds_dwordx4 v[230:231], off
	v_lshl_add_u64 v[230:231], s[28:29], 0, v[136:137]
	s_add_i32 m0, s30, 0x2000
	s_nop 0
	global_load_lds_dwordx4 v[230:231], off
	v_lshl_add_u64 v[230:231], v[234:235], 0, s[12:13]
	s_mov_b32 m0, s40
	s_nop 0
	global_load_lds_dwordx4 v[230:231], off
	v_lshl_add_u64 v[230:231], v[236:237], 0, s[12:13]
	s_mov_b32 m0, s41
	s_nop 0
	global_load_lds_dwordx4 v[230:231], off
	s_waitcnt vmcnt(8)
	s_waitcnt lgkmcnt(0)
	s_barrier
	s_setprio 1
	v_mfma_f32_16x16x32_bf16 v[60:63], v[162:165], v[196:199], v[60:63]
	v_mfma_f32_16x16x32_bf16 v[52:55], v[170:173], v[196:199], v[52:55]
	v_mfma_f32_16x16x32_bf16 v[44:47], v[162:165], v[204:207], v[44:47]
	v_mfma_f32_16x16x32_bf16 v[36:39], v[170:173], v[204:207], v[36:39]
	v_mfma_f32_16x16x32_bf16 v[28:31], v[162:165], v[214:217], v[28:31]
	v_mfma_f32_16x16x32_bf16 v[20:23], v[170:173], v[214:217], v[20:23]
	v_mfma_f32_16x16x32_bf16 v[12:15], v[162:165], v[222:225], v[12:15]
	v_mfma_f32_16x16x32_bf16 v[4:7], v[170:173], v[222:225], v[4:7]
	v_mfma_f32_16x16x32_bf16 v[60:63], v[166:169], v[200:203], v[60:63]
	v_mfma_f32_16x16x32_bf16 v[52:55], v[174:177], v[200:203], v[52:55]
	v_mfma_f32_16x16x32_bf16 v[44:47], v[166:169], v[210:213], v[44:47]
	v_mfma_f32_16x16x32_bf16 v[36:39], v[174:177], v[210:213], v[36:39]
	v_mfma_f32_16x16x32_bf16 v[28:31], v[166:169], v[218:221], v[28:31]
	v_mfma_f32_16x16x32_bf16 v[20:23], v[174:177], v[218:221], v[20:23]
	v_mfma_f32_16x16x32_bf16 v[12:15], v[166:169], v[226:229], v[12:15]
	v_mfma_f32_16x16x32_bf16 v[4:7], v[174:177], v[226:229], v[4:7]
	v_mfma_f32_16x16x32_bf16 v[56:59], v[180:183], v[196:199], v[56:59]
	v_mfma_f32_16x16x32_bf16 v[48:51], v[188:191], v[196:199], v[48:51]
	v_mfma_f32_16x16x32_bf16 v[40:43], v[180:183], v[204:207], v[40:43]
	v_mfma_f32_16x16x32_bf16 v[32:35], v[188:191], v[204:207], v[32:35]
	v_mfma_f32_16x16x32_bf16 v[24:27], v[180:183], v[214:217], v[24:27]
	v_mfma_f32_16x16x32_bf16 v[16:19], v[188:191], v[214:217], v[16:19]
	v_mfma_f32_16x16x32_bf16 v[8:11], v[180:183], v[222:225], v[8:11]
	v_mfma_f32_16x16x32_bf16 v[0:3], v[188:191], v[222:225], v[0:3]
	v_mfma_f32_16x16x32_bf16 v[56:59], v[184:187], v[200:203], v[56:59]
	v_mfma_f32_16x16x32_bf16 v[48:51], v[192:195], v[200:203], v[48:51]
	v_mfma_f32_16x16x32_bf16 v[40:43], v[184:187], v[210:213], v[40:43]
	v_mfma_f32_16x16x32_bf16 v[32:35], v[192:195], v[210:213], v[32:35]
	v_mfma_f32_16x16x32_bf16 v[24:27], v[184:187], v[218:221], v[24:27]
	v_mfma_f32_16x16x32_bf16 v[16:19], v[192:195], v[218:221], v[16:19]
	v_mfma_f32_16x16x32_bf16 v[8:11], v[184:187], v[226:229], v[8:11]
	v_mfma_f32_16x16x32_bf16 v[0:3], v[192:195], v[226:229], v[0:3]
	s_setprio 0
	s_barrier
	s_add_i32 s49, s49, 2
	s_add_u32 s26, s26, 0x100
	s_addc_u32 s27, s27, 0
	s_add_u32 s47, s47, 0x100
	s_addc_u32 s48, s48, 0
	s_cmp_gt_u32 s49, 29
	s_cbranch_scc0 .LBB0_1298
	s_and_b64 vcc, exec, s[14:15]
	s_cbranch_vccz .LBB0_1301
	s_barrier

.LBB0_1327:
	s_add_u32 s25, s28, s23
	s_addc_u32 s27, s29, 0
	s_add_u32 s37, s25, 0x100
	s_addc_u32 s44, s27, 0
	s_and_b64 s[42:43], s[40:41], exec
	s_cselect_b32 s45, s31, s44
	s_cselect_b32 s44, s30, s37
	s_add_u32 s23, s20, s23
	s_addc_u32 s37, s21, 0
	s_add_u32 s23, s23, 0x100
	s_addc_u32 s37, s37, 0
	s_and_b64 s[40:41], s[40:41], exec
	s_cselect_b32 s47, s35, s37
	s_cselect_b32 s46, s34, s23
	s_add_u32 s50, s25, 0x80080
	s_addc_u32 s51, s27, 0
	s_add_i32 s84, s63, s2
	ds_read_b128 v[156:159], v129
	ds_read_b128 v[160:163], v129 offset:1024
	ds_read_b128 v[164:167], v129 offset:2048
	ds_read_b128 v[168:171], v129 offset:3072
	ds_read_b128 v[172:175], v141
	ds_read_b128 v[180:183], v141 offset:1024
	ds_read_b128 v[184:187], v141 offset:2048
	ds_read_b128 v[188:191], v141 offset:3072
	s_add_i32 m0, s3, 0xc000
	s_add_i32 s85, s3, 0xe000
	s_add_i32 s81, s84, 0x2000
	s_add_u32 s48, s46, 0x80000
	s_addc_u32 s49, s47, 0
	s_add_i32 s83, s64, s2
	s_add_i32 s82, s83, 0x2000
	s_add_i32 s80, 0, 0x18000
	s_add_i32 s79, 0, 0x1c000
	s_add_u32 s42, s44, 0x80000
	s_addc_u32 s43, s45, 0
	s_add_i32 s37, s80, s2
	s_add_i32 s25, s37, 0x2000
	s_add_u32 s40, s46, 0x80080
	s_addc_u32 s41, s47, 0
	s_add_i32 s27, s79, s2
	s_add_i32 s23, s27, 0x2000
	v_lshl_add_u64 v[176:177], s[50:51], 0, v[130:131]
	ds_read_b128 v[192:195], v142
	ds_read_b128 v[196:199], v142 offset:1024
	ds_read_b128 v[200:203], v142 offset:2048
	ds_read_b128 v[204:207], v142 offset:3072
	ds_read_b128 v[210:213], v142 offset:4096
	ds_read_b128 v[214:217], v142 offset:5120
	ds_read_b128 v[218:221], v142 offset:6144
	ds_read_b128 v[222:225], v142 offset:7168
	global_load_lds_dwordx4 v[176:177], off
	v_lshl_add_u64 v[176:177], s[50:51], 0, v[134:135]
	s_mov_b32 m0, s85
	s_nop 0
	global_load_lds_dwordx4 v[176:177], off
	s_waitcnt vmcnt(8)
	s_waitcnt lgkmcnt(0)
	s_barrier
	s_setprio 1
	v_mfma_f32_16x16x32_bf16 v[124:127], v[156:159], v[192:195], v[124:127]
	v_mfma_f32_16x16x32_bf16 v[120:123], v[164:167], v[192:195], v[120:123]
	v_mfma_f32_16x16x32_bf16 v[116:119], v[156:159], v[200:203], v[116:119]
	v_mfma_f32_16x16x32_bf16 v[112:115], v[164:167], v[200:203], v[112:115]
	v_mfma_f32_16x16x32_bf16 v[108:111], v[156:159], v[210:213], v[108:111]
	v_mfma_f32_16x16x32_bf16 v[104:107], v[164:167], v[210:213], v[104:107]
	v_mfma_f32_16x16x32_bf16 v[100:103], v[156:159], v[218:221], v[100:103]
	v_mfma_f32_16x16x32_bf16 v[96:99], v[164:167], v[218:221], v[96:99]
	v_mfma_f32_16x16x32_bf16 v[124:127], v[160:163], v[196:199], v[124:127]
	v_mfma_f32_16x16x32_bf16 v[120:123], v[168:171], v[196:199], v[120:123]
	v_mfma_f32_16x16x32_bf16 v[116:119], v[160:163], v[204:207], v[116:119]
	v_mfma_f32_16x16x32_bf16 v[112:115], v[168:171], v[204:207], v[112:115]
	v_mfma_f32_16x16x32_bf16 v[108:111], v[160:163], v[214:217], v[108:111]
	v_mfma_f32_16x16x32_bf16 v[104:107], v[168:171], v[214:217], v[104:107]
	v_mfma_f32_16x16x32_bf16 v[100:103], v[160:163], v[222:225], v[100:103]
	v_mfma_f32_16x16x32_bf16 v[96:99], v[168:171], v[222:225], v[96:99]
	v_mfma_f32_16x16x32_bf16 v[92:95], v[172:175], v[192:195], v[92:95]
	v_mfma_f32_16x16x32_bf16 v[88:91], v[184:187], v[192:195], v[88:91]
	v_mfma_f32_16x16x32_bf16 v[84:87], v[172:175], v[200:203], v[84:87]
	v_mfma_f32_16x16x32_bf16 v[80:83], v[184:187], v[200:203], v[80:83]
	v_mfma_f32_16x16x32_bf16 v[76:79], v[172:175], v[210:213], v[76:79]
	v_mfma_f32_16x16x32_bf16 v[72:75], v[184:187], v[210:213], v[72:75]
	v_mfma_f32_16x16x32_bf16 v[68:71], v[172:175], v[218:221], v[68:71]
	v_mfma_f32_16x16x32_bf16 v[64:67], v[184:187], v[218:221], v[64:67]
	v_mfma_f32_16x16x32_bf16 v[92:95], v[180:183], v[196:199], v[92:95]
	v_mfma_f32_16x16x32_bf16 v[88:91], v[188:191], v[196:199], v[88:91]
	v_mfma_f32_16x16x32_bf16 v[84:87], v[180:183], v[204:207], v[84:87]
	v_mfma_f32_16x16x32_bf16 v[80:83], v[188:191], v[204:207], v[80:83]
	v_mfma_f32_16x16x32_bf16 v[76:79], v[180:183], v[214:217], v[76:79]
	v_mfma_f32_16x16x32_bf16 v[72:75], v[188:191], v[214:217], v[72:75]
	v_mfma_f32_16x16x32_bf16 v[68:71], v[180:183], v[222:225], v[68:71]
	v_mfma_f32_16x16x32_bf16 v[64:67], v[188:191], v[222:225], v[64:67]
	s_setprio 0
	s_barrier
	s_mov_b32 m0, s84
	v_lshl_add_u64 v[176:177], s[46:47], 0, v[132:133]
	ds_read_b128 v[192:195], v142 offset:16384
	ds_read_b128 v[196:199], v142 offset:17408
	ds_read_b128 v[200:203], v142 offset:18432
	ds_read_b128 v[204:207], v142 offset:19456
	ds_read_b128 v[210:213], v142 offset:20480
	ds_read_b128 v[214:217], v142 offset:21504
	ds_read_b128 v[218:221], v142 offset:22528
	ds_read_b128 v[222:225], v142 offset:23552
	global_load_lds_dwordx4 v[176:177], off
	v_lshl_add_u64 v[226:227], s[46:47], 0, v[136:137]
	s_mov_b32 m0, s81
	v_lshl_add_u64 v[228:229], s[48:49], 0, v[132:133]
	global_load_lds_dwordx4 v[226:227], off
	s_mov_b32 m0, s83
	v_lshl_add_u64 v[230:231], s[44:45], 0, v[134:135]
	global_load_lds_dwordx4 v[228:229], off
	v_lshl_add_u64 v[228:229], s[48:49], 0, v[136:137]
	s_mov_b32 m0, s82
	s_nop 0
	global_load_lds_dwordx4 v[228:229], off
	v_lshl_add_u64 v[228:229], s[44:45], 0, v[130:131]
	s_mov_b32 m0, s3
	s_nop 0
	global_load_lds_dwordx4 v[228:229], off
	s_mov_b32 m0, s56
	s_nop 0
	global_load_lds_dwordx4 v[230:231], off
	s_waitcnt vmcnt(8)
	s_waitcnt lgkmcnt(0)
	s_barrier
	s_setprio 1
	v_mfma_f32_16x16x32_bf16 v[60:63], v[156:159], v[192:195], v[60:63]
	v_mfma_f32_16x16x32_bf16 v[56:59], v[164:167], v[192:195], v[56:59]
	v_mfma_f32_16x16x32_bf16 v[52:55], v[156:159], v[200:203], v[52:55]
	v_mfma_f32_16x16x32_bf16 v[48:51], v[164:167], v[200:203], v[48:51]
	v_mfma_f32_16x16x32_bf16 v[44:47], v[156:159], v[210:213], v[44:47]
	v_mfma_f32_16x16x32_bf16 v[40:43], v[164:167], v[210:213], v[40:43]
	v_mfma_f32_16x16x32_bf16 v[36:39], v[156:159], v[218:221], v[36:39]
	v_mfma_f32_16x16x32_bf16 v[32:35], v[164:167], v[218:221], v[32:35]
	v_mfma_f32_16x16x32_bf16 v[60:63], v[160:163], v[196:199], v[60:63]
	v_mfma_f32_16x16x32_bf16 v[56:59], v[168:171], v[196:199], v[56:59]
	v_mfma_f32_16x16x32_bf16 v[52:55], v[160:163], v[204:207], v[52:55]
	v_mfma_f32_16x16x32_bf16 v[48:51], v[168:171], v[204:207], v[48:51]
	v_mfma_f32_16x16x32_bf16 v[44:47], v[160:163], v[214:217], v[44:47]
	v_mfma_f32_16x16x32_bf16 v[40:43], v[168:171], v[214:217], v[40:43]
	v_mfma_f32_16x16x32_bf16 v[36:39], v[160:163], v[222:225], v[36:39]
	v_mfma_f32_16x16x32_bf16 v[32:35], v[168:171], v[222:225], v[32:35]
	v_mfma_f32_16x16x32_bf16 v[28:31], v[172:175], v[192:195], v[28:31]
	v_mfma_f32_16x16x32_bf16 v[24:27], v[184:187], v[192:195], v[24:27]
	v_mfma_f32_16x16x32_bf16 v[20:23], v[172:175], v[200:203], v[20:23]
	v_mfma_f32_16x16x32_bf16 v[16:19], v[184:187], v[200:203], v[16:19]
	v_mfma_f32_16x16x32_bf16 v[12:15], v[172:175], v[210:213], v[12:15]
	v_mfma_f32_16x16x32_bf16 v[8:11], v[184:187], v[210:213], v[8:11]
	v_mfma_f32_16x16x32_bf16 v[4:7], v[172:175], v[218:221], v[4:7]
	v_mfma_f32_16x16x32_bf16 v[0:3], v[184:187], v[218:221], v[0:3]
	v_mfma_f32_16x16x32_bf16 v[28:31], v[180:183], v[196:199], v[28:31]
	v_mfma_f32_16x16x32_bf16 v[24:27], v[188:191], v[196:199], v[24:27]
	v_mfma_f32_16x16x32_bf16 v[20:23], v[180:183], v[204:207], v[20:23]
	v_mfma_f32_16x16x32_bf16 v[16:19], v[188:191], v[204:207], v[16:19]
	v_mfma_f32_16x16x32_bf16 v[12:15], v[180:183], v[214:217], v[12:15]
	v_mfma_f32_16x16x32_bf16 v[8:11], v[188:191], v[214:217], v[8:11]
	v_mfma_f32_16x16x32_bf16 v[4:7], v[180:183], v[222:225], v[4:7]
	v_mfma_f32_16x16x32_bf16 v[0:3], v[188:191], v[222:225], v[0:3]
	s_setprio 0
	s_barrier
	v_add_u32_e32 v143, s80, v140
	ds_read_b128 v[156:159], v143
	ds_read_b128 v[160:163], v143 offset:1024
	ds_read_b128 v[164:167], v143 offset:2048
	ds_read_b128 v[168:171], v143 offset:3072
	v_add_u32_e32 v143, s79, v140
	ds_read_b128 v[172:175], v143
	ds_read_b128 v[180:183], v143 offset:1024
	ds_read_b128 v[184:187], v143 offset:2048
	ds_read_b128 v[188:191], v143 offset:3072
	s_mov_b32 m0, s57
	v_lshl_add_u64 v[232:233], s[42:43], 0, v[130:131]
	ds_read_b128 v[192:195], v142 offset:32768
	ds_read_b128 v[196:199], v142 offset:33792
	ds_read_b128 v[200:203], v142 offset:34816
	ds_read_b128 v[204:207], v142 offset:35840
	ds_read_b128 v[210:213], v142 offset:36864
	ds_read_b128 v[214:217], v142 offset:37888
	ds_read_b128 v[218:221], v142 offset:38912
	ds_read_b128 v[222:225], v142 offset:39936
	global_load_lds_dwordx4 v[232:233], off
	v_lshl_add_u64 v[232:233], s[42:43], 0, v[134:135]
	s_mov_b32 m0, s58
	s_nop 0
	global_load_lds_dwordx4 v[232:233], off
	s_waitcnt vmcnt(8)
	s_waitcnt lgkmcnt(0)
	s_barrier
	s_setprio 1
	v_mfma_f32_16x16x32_bf16 v[124:127], v[156:159], v[192:195], v[124:127]
	v_mfma_f32_16x16x32_bf16 v[120:123], v[164:167], v[192:195], v[120:123]
	v_mfma_f32_16x16x32_bf16 v[116:119], v[156:159], v[200:203], v[116:119]
	v_mfma_f32_16x16x32_bf16 v[112:115], v[164:167], v[200:203], v[112:115]
	v_mfma_f32_16x16x32_bf16 v[108:111], v[156:159], v[210:213], v[108:111]
	v_mfma_f32_16x16x32_bf16 v[104:107], v[164:167], v[210:213], v[104:107]
	v_mfma_f32_16x16x32_bf16 v[100:103], v[156:159], v[218:221], v[100:103]
	v_mfma_f32_16x16x32_bf16 v[96:99], v[164:167], v[218:221], v[96:99]
	v_mfma_f32_16x16x32_bf16 v[124:127], v[160:163], v[196:199], v[124:127]
	v_mfma_f32_16x16x32_bf16 v[120:123], v[168:171], v[196:199], v[120:123]
	v_mfma_f32_16x16x32_bf16 v[116:119], v[160:163], v[204:207], v[116:119]
	v_mfma_f32_16x16x32_bf16 v[112:115], v[168:171], v[204:207], v[112:115]
	v_mfma_f32_16x16x32_bf16 v[108:111], v[160:163], v[214:217], v[108:111]
	v_mfma_f32_16x16x32_bf16 v[104:107], v[168:171], v[214:217], v[104:107]
	v_mfma_f32_16x16x32_bf16 v[100:103], v[160:163], v[222:225], v[100:103]
	v_mfma_f32_16x16x32_bf16 v[96:99], v[168:171], v[222:225], v[96:99]
	v_mfma_f32_16x16x32_bf16 v[92:95], v[172:175], v[192:195], v[92:95]
	v_mfma_f32_16x16x32_bf16 v[88:91], v[184:187], v[192:195], v[88:91]
	v_mfma_f32_16x16x32_bf16 v[84:87], v[172:175], v[200:203], v[84:87]
	v_mfma_f32_16x16x32_bf16 v[80:83], v[184:187], v[200:203], v[80:83]
	v_mfma_f32_16x16x32_bf16 v[76:79], v[172:175], v[210:213], v[76:79]
	v_mfma_f32_16x16x32_bf16 v[72:75], v[184:187], v[210:213], v[72:75]
	v_mfma_f32_16x16x32_bf16 v[68:71], v[172:175], v[218:221], v[68:71]
	v_mfma_f32_16x16x32_bf16 v[64:67], v[184:187], v[218:221], v[64:67]
	v_mfma_f32_16x16x32_bf16 v[92:95], v[180:183], v[196:199], v[92:95]
	v_mfma_f32_16x16x32_bf16 v[88:91], v[188:191], v[196:199], v[88:91]
	v_mfma_f32_16x16x32_bf16 v[84:87], v[180:183], v[204:207], v[84:87]
	v_mfma_f32_16x16x32_bf16 v[80:83], v[188:191], v[204:207], v[80:83]
	v_mfma_f32_16x16x32_bf16 v[76:79], v[180:183], v[214:217], v[76:79]
	v_mfma_f32_16x16x32_bf16 v[72:75], v[188:191], v[214:217], v[72:75]
	v_mfma_f32_16x16x32_bf16 v[68:71], v[180:183], v[222:225], v[68:71]
	v_mfma_f32_16x16x32_bf16 v[64:67], v[188:191], v[222:225], v[64:67]
	s_setprio 0
	s_barrier
	s_mov_b32 m0, s37
	v_lshl_add_u64 v[176:177], v[176:177], 0, s[16:17]
	ds_read_b128 v[192:195], v142 offset:49152
	ds_read_b128 v[196:199], v142 offset:50176
	ds_read_b128 v[200:203], v142 offset:51200
	ds_read_b128 v[204:207], v142 offset:52224
	ds_read_b128 v[210:213], v142 offset:53248
	ds_read_b128 v[214:217], v142 offset:54272
	ds_read_b128 v[218:221], v142 offset:55296
	ds_read_b128 v[222:225], v142 offset:56320
	global_load_lds_dwordx4 v[176:177], off
	v_lshl_add_u64 v[176:177], v[226:227], 0, s[16:17]
	s_mov_b32 m0, s25
	s_nop 0
	global_load_lds_dwordx4 v[176:177], off
	v_lshl_add_u64 v[176:177], s[40:41], 0, v[132:133]
	s_mov_b32 m0, s27
	s_nop 0
	global_load_lds_dwordx4 v[176:177], off
	v_lshl_add_u64 v[176:177], s[40:41], 0, v[136:137]
	s_mov_b32 m0, s23
	s_nop 0
	global_load_lds_dwordx4 v[176:177], off
	v_lshl_add_u64 v[176:177], v[228:229], 0, s[16:17]
	s_mov_b32 m0, s60
	s_nop 0
	global_load_lds_dwordx4 v[176:177], off
	v_lshl_add_u64 v[176:177], v[230:231], 0, s[16:17]
	s_mov_b32 m0, s61
	s_nop 0
	global_load_lds_dwordx4 v[176:177], off
	s_waitcnt vmcnt(8)
	s_waitcnt lgkmcnt(0)
	s_barrier
	s_setprio 1
	v_mfma_f32_16x16x32_bf16 v[60:63], v[156:159], v[192:195], v[60:63]
	v_mfma_f32_16x16x32_bf16 v[56:59], v[164:167], v[192:195], v[56:59]
	v_mfma_f32_16x16x32_bf16 v[52:55], v[156:159], v[200:203], v[52:55]
	v_mfma_f32_16x16x32_bf16 v[48:51], v[164:167], v[200:203], v[48:51]
	v_mfma_f32_16x16x32_bf16 v[44:47], v[156:159], v[210:213], v[44:47]
	v_mfma_f32_16x16x32_bf16 v[40:43], v[164:167], v[210:213], v[40:43]
	v_mfma_f32_16x16x32_bf16 v[36:39], v[156:159], v[218:221], v[36:39]
	v_mfma_f32_16x16x32_bf16 v[32:35], v[164:167], v[218:221], v[32:35]
	v_mfma_f32_16x16x32_bf16 v[60:63], v[160:163], v[196:199], v[60:63]
	v_mfma_f32_16x16x32_bf16 v[56:59], v[168:171], v[196:199], v[56:59]
	v_mfma_f32_16x16x32_bf16 v[52:55], v[160:163], v[204:207], v[52:55]
	v_mfma_f32_16x16x32_bf16 v[48:51], v[168:171], v[204:207], v[48:51]
	v_mfma_f32_16x16x32_bf16 v[44:47], v[160:163], v[214:217], v[44:47]
	v_mfma_f32_16x16x32_bf16 v[40:43], v[168:171], v[214:217], v[40:43]
	v_mfma_f32_16x16x32_bf16 v[36:39], v[160:163], v[222:225], v[36:39]
	v_mfma_f32_16x16x32_bf16 v[32:35], v[168:171], v[222:225], v[32:35]
	v_mfma_f32_16x16x32_bf16 v[28:31], v[172:175], v[192:195], v[28:31]
	v_mfma_f32_16x16x32_bf16 v[24:27], v[184:187], v[192:195], v[24:27]
	v_mfma_f32_16x16x32_bf16 v[20:23], v[172:175], v[200:203], v[20:23]
	v_mfma_f32_16x16x32_bf16 v[16:19], v[184:187], v[200:203], v[16:19]
	v_mfma_f32_16x16x32_bf16 v[12:15], v[172:175], v[210:213], v[12:15]
	v_mfma_f32_16x16x32_bf16 v[8:11], v[184:187], v[210:213], v[8:11]
	v_mfma_f32_16x16x32_bf16 v[4:7], v[172:175], v[218:221], v[4:7]
	v_mfma_f32_16x16x32_bf16 v[0:3], v[184:187], v[218:221], v[0:3]
	v_mfma_f32_16x16x32_bf16 v[28:31], v[180:183], v[196:199], v[28:31]
	v_mfma_f32_16x16x32_bf16 v[24:27], v[188:191], v[196:199], v[24:27]
	v_mfma_f32_16x16x32_bf16 v[20:23], v[180:183], v[204:207], v[20:23]
	v_mfma_f32_16x16x32_bf16 v[16:19], v[188:191], v[204:207], v[16:19]
	v_mfma_f32_16x16x32_bf16 v[12:15], v[180:183], v[214:217], v[12:15]
	v_mfma_f32_16x16x32_bf16 v[8:11], v[188:191], v[214:217], v[8:11]
	v_mfma_f32_16x16x32_bf16 v[4:7], v[180:183], v[222:225], v[4:7]
	v_mfma_f32_16x16x32_bf16 v[0:3], v[188:191], v[222:225], v[0:3]
	s_setprio 0
	s_barrier
	s_movk_i32 s23, 0x100
	s_andn2_b64 vcc, exec, s[38:39]
	s_mov_b64 s[40:41], -1
	s_mov_b64 s[38:39], 0
	s_cbranch_vccz .LBB0_1327
	s_and_b64 vcc, exec, s[18:19]
	s_cbranch_vccz .LBB0_1330
	s_barrier

.LBB0_1461:
	ds_read_b128 v[144:147], v158
	ds_read_b128 v[162:165], v158 offset:1024
	ds_read_b128 v[166:169], v158 offset:2048
	ds_read_b128 v[170:173], v158 offset:3072
	ds_read_b128 v[174:177], v159
	ds_read_b128 v[180:183], v159 offset:1024
	ds_read_b128 v[184:187], v159 offset:2048
	ds_read_b128 v[188:191], v159 offset:3072
	s_add_u32 s22, s20, 0xffea0080
	s_addc_u32 s23, s21, -1
	s_cmpk_eq_i32 s47, 0x54
	s_cselect_b32 s25, s1, s23
	s_cselect_b32 s24, s0, s22
	s_cselect_b32 s23, s19, s46
	s_cselect_b32 s22, s18, s45
	v_lshl_add_u64 v[226:227], s[20:21], 0, v[138:139]
	s_add_i32 m0, s3, 0xc000
	ds_read_b128 v[192:195], v160
	ds_read_b128 v[196:199], v160 offset:1024
	ds_read_b128 v[200:203], v160 offset:2048
	ds_read_b128 v[204:207], v160 offset:3072
	ds_read_b128 v[210:213], v160 offset:4096
	ds_read_b128 v[214:217], v160 offset:5120
	ds_read_b128 v[218:221], v160 offset:6144
	ds_read_b128 v[222:225], v160 offset:7168
	global_load_lds_dwordx4 v[226:227], off
	v_lshl_add_u64 v[226:227], s[20:21], 0, v[140:141]
	s_add_i32 m0, s3, 0xe000
	s_nop 0
	global_load_lds_dwordx4 v[226:227], off
	s_waitcnt vmcnt(8)
	s_waitcnt lgkmcnt(0)
	s_barrier
	s_setprio 1
	v_mfma_f32_16x16x32_bf16 v[124:127], v[144:147], v[192:195], v[124:127]
	v_mfma_f32_16x16x32_bf16 v[120:123], v[166:169], v[192:195], v[120:123]
	v_mfma_f32_16x16x32_bf16 v[108:111], v[144:147], v[200:203], v[108:111]
	v_mfma_f32_16x16x32_bf16 v[104:107], v[166:169], v[200:203], v[104:107]
	v_mfma_f32_16x16x32_bf16 v[92:95], v[144:147], v[210:213], v[92:95]
	v_mfma_f32_16x16x32_bf16 v[88:91], v[166:169], v[210:213], v[88:91]
	v_mfma_f32_16x16x32_bf16 v[76:79], v[144:147], v[218:221], v[76:79]
	v_mfma_f32_16x16x32_bf16 v[72:75], v[166:169], v[218:221], v[72:75]
	v_mfma_f32_16x16x32_bf16 v[124:127], v[162:165], v[196:199], v[124:127]
	v_mfma_f32_16x16x32_bf16 v[120:123], v[170:173], v[196:199], v[120:123]
	v_mfma_f32_16x16x32_bf16 v[108:111], v[162:165], v[204:207], v[108:111]
	v_mfma_f32_16x16x32_bf16 v[104:107], v[170:173], v[204:207], v[104:107]
	v_mfma_f32_16x16x32_bf16 v[92:95], v[162:165], v[214:217], v[92:95]
	v_mfma_f32_16x16x32_bf16 v[88:91], v[170:173], v[214:217], v[88:91]
	v_mfma_f32_16x16x32_bf16 v[76:79], v[162:165], v[222:225], v[76:79]
	v_mfma_f32_16x16x32_bf16 v[72:75], v[170:173], v[222:225], v[72:75]
	v_mfma_f32_16x16x32_bf16 v[116:119], v[174:177], v[192:195], v[116:119]
	v_mfma_f32_16x16x32_bf16 v[112:115], v[184:187], v[192:195], v[112:115]
	v_mfma_f32_16x16x32_bf16 v[100:103], v[174:177], v[200:203], v[100:103]
	v_mfma_f32_16x16x32_bf16 v[96:99], v[184:187], v[200:203], v[96:99]
	v_mfma_f32_16x16x32_bf16 v[84:87], v[174:177], v[210:213], v[84:87]
	v_mfma_f32_16x16x32_bf16 v[80:83], v[184:187], v[210:213], v[80:83]
	v_mfma_f32_16x16x32_bf16 v[68:71], v[174:177], v[218:221], v[68:71]
	v_mfma_f32_16x16x32_bf16 v[64:67], v[184:187], v[218:221], v[64:67]
	v_mfma_f32_16x16x32_bf16 v[116:119], v[180:183], v[196:199], v[116:119]
	v_mfma_f32_16x16x32_bf16 v[112:115], v[188:191], v[196:199], v[112:115]
	v_mfma_f32_16x16x32_bf16 v[100:103], v[180:183], v[204:207], v[100:103]
	v_mfma_f32_16x16x32_bf16 v[96:99], v[188:191], v[204:207], v[96:99]
	v_mfma_f32_16x16x32_bf16 v[84:87], v[180:183], v[214:217], v[84:87]
	v_mfma_f32_16x16x32_bf16 v[80:83], v[188:191], v[214:217], v[80:83]
	v_mfma_f32_16x16x32_bf16 v[68:71], v[180:183], v[222:225], v[68:71]
	v_mfma_f32_16x16x32_bf16 v[64:67], v[188:191], v[222:225], v[64:67]
	s_setprio 0
	s_barrier
	s_add_i32 s48, s39, s26
	v_lshl_add_u64 v[226:227], s[22:23], 0, v[132:133]
	s_mov_b32 m0, s48
	ds_read_b128 v[192:195], v160 offset:16384
	ds_read_b128 v[196:199], v160 offset:17408
	ds_read_b128 v[200:203], v160 offset:18432
	ds_read_b128 v[204:207], v160 offset:19456
	ds_read_b128 v[210:213], v160 offset:20480
	ds_read_b128 v[214:217], v160 offset:21504
	ds_read_b128 v[218:221], v160 offset:22528
	ds_read_b128 v[222:225], v160 offset:23552
	global_load_lds_dwordx4 v[226:227], off
	s_add_i32 m0, s48, 0x2000
	s_add_u32 s48, s22, 0x160000
	v_lshl_add_u64 v[228:229], s[22:23], 0, v[136:137]
	s_addc_u32 s49, s23, 0
	s_add_i32 s50, s40, s26
	global_load_lds_dwordx4 v[228:229], off
	v_lshl_add_u64 v[230:231], s[48:49], 0, v[132:133]
	s_mov_b32 m0, s50
	v_lshl_add_u64 v[232:233], s[24:25], 0, v[134:135]
	global_load_lds_dwordx4 v[230:231], off
	v_lshl_add_u64 v[230:231], s[48:49], 0, v[136:137]
	s_add_i32 m0, s50, 0x2000
	s_nop 0
	global_load_lds_dwordx4 v[230:231], off
	v_lshl_add_u64 v[230:231], s[24:25], 0, v[130:131]
	s_mov_b32 m0, s3
	s_nop 0
	global_load_lds_dwordx4 v[230:231], off
	s_mov_b32 m0, s28
	s_nop 0
	global_load_lds_dwordx4 v[232:233], off
	s_waitcnt vmcnt(8)
	s_waitcnt lgkmcnt(0)
	s_barrier
	s_setprio 1
	v_mfma_f32_16x16x32_bf16 v[60:63], v[144:147], v[192:195], v[60:63]
	v_mfma_f32_16x16x32_bf16 v[56:59], v[166:169], v[192:195], v[56:59]
	v_mfma_f32_16x16x32_bf16 v[44:47], v[144:147], v[200:203], v[44:47]
	v_mfma_f32_16x16x32_bf16 v[40:43], v[166:169], v[200:203], v[40:43]
	v_mfma_f32_16x16x32_bf16 v[28:31], v[144:147], v[210:213], v[28:31]
	v_mfma_f32_16x16x32_bf16 v[24:27], v[166:169], v[210:213], v[24:27]
	v_mfma_f32_16x16x32_bf16 v[12:15], v[144:147], v[218:221], v[12:15]
	v_mfma_f32_16x16x32_bf16 v[8:11], v[166:169], v[218:221], v[8:11]
	v_mfma_f32_16x16x32_bf16 v[60:63], v[162:165], v[196:199], v[60:63]
	v_mfma_f32_16x16x32_bf16 v[56:59], v[170:173], v[196:199], v[56:59]
	v_mfma_f32_16x16x32_bf16 v[44:47], v[162:165], v[204:207], v[44:47]
	v_mfma_f32_16x16x32_bf16 v[40:43], v[170:173], v[204:207], v[40:43]
	v_mfma_f32_16x16x32_bf16 v[28:31], v[162:165], v[214:217], v[28:31]
	v_mfma_f32_16x16x32_bf16 v[24:27], v[170:173], v[214:217], v[24:27]
	v_mfma_f32_16x16x32_bf16 v[12:15], v[162:165], v[222:225], v[12:15]
	v_mfma_f32_16x16x32_bf16 v[8:11], v[170:173], v[222:225], v[8:11]
	v_mfma_f32_16x16x32_bf16 v[52:55], v[174:177], v[192:195], v[52:55]
	v_mfma_f32_16x16x32_bf16 v[48:51], v[184:187], v[192:195], v[48:51]
	v_mfma_f32_16x16x32_bf16 v[36:39], v[174:177], v[200:203], v[36:39]
	v_mfma_f32_16x16x32_bf16 v[32:35], v[184:187], v[200:203], v[32:35]
	v_mfma_f32_16x16x32_bf16 v[20:23], v[174:177], v[210:213], v[20:23]
	v_mfma_f32_16x16x32_bf16 v[16:19], v[184:187], v[210:213], v[16:19]
	v_mfma_f32_16x16x32_bf16 v[4:7], v[174:177], v[218:221], v[4:7]
	v_mfma_f32_16x16x32_bf16 v[0:3], v[184:187], v[218:221], v[0:3]
	v_mfma_f32_16x16x32_bf16 v[52:55], v[180:183], v[196:199], v[52:55]
	v_mfma_f32_16x16x32_bf16 v[48:51], v[188:191], v[196:199], v[48:51]
	v_mfma_f32_16x16x32_bf16 v[36:39], v[180:183], v[204:207], v[36:39]
	v_mfma_f32_16x16x32_bf16 v[32:35], v[188:191], v[204:207], v[32:35]
	v_mfma_f32_16x16x32_bf16 v[20:23], v[180:183], v[214:217], v[20:23]
	v_mfma_f32_16x16x32_bf16 v[16:19], v[188:191], v[214:217], v[16:19]
	v_mfma_f32_16x16x32_bf16 v[4:7], v[180:183], v[222:225], v[4:7]
	v_mfma_f32_16x16x32_bf16 v[0:3], v[188:191], v[222:225], v[0:3]
	s_setprio 0
	s_barrier
	s_add_i32 s48, 0, 0x18000
	v_add_u32_e32 v161, s48, v156
	s_add_i32 s49, 0, 0x1c000
	ds_read_b128 v[144:147], v161
	ds_read_b128 v[162:165], v161 offset:1024
	ds_read_b128 v[166:169], v161 offset:2048
	ds_read_b128 v[170:173], v161 offset:3072
	v_add_u32_e32 v161, s49, v156
	ds_read_b128 v[174:177], v161
	ds_read_b128 v[180:183], v161 offset:1024
	ds_read_b128 v[184:187], v161 offset:2048
	ds_read_b128 v[188:191], v161 offset:3072
	s_add_u32 s24, s24, 0x160000
	s_addc_u32 s25, s25, 0
	s_mov_b32 m0, s29
	v_lshl_add_u64 v[234:235], s[24:25], 0, v[130:131]
	ds_read_b128 v[192:195], v160 offset:32768
	ds_read_b128 v[196:199], v160 offset:33792
	ds_read_b128 v[200:203], v160 offset:34816
	ds_read_b128 v[204:207], v160 offset:35840
	ds_read_b128 v[210:213], v160 offset:36864
	ds_read_b128 v[214:217], v160 offset:37888
	ds_read_b128 v[218:221], v160 offset:38912
	ds_read_b128 v[222:225], v160 offset:39936
	global_load_lds_dwordx4 v[234:235], off
	v_lshl_add_u64 v[234:235], s[24:25], 0, v[134:135]
	s_mov_b32 m0, s36
	s_nop 0
	global_load_lds_dwordx4 v[234:235], off
	s_waitcnt vmcnt(8)
	s_waitcnt lgkmcnt(0)
	s_barrier
	s_setprio 1
	v_mfma_f32_16x16x32_bf16 v[124:127], v[144:147], v[192:195], v[124:127]
	v_mfma_f32_16x16x32_bf16 v[120:123], v[166:169], v[192:195], v[120:123]
	v_mfma_f32_16x16x32_bf16 v[108:111], v[144:147], v[200:203], v[108:111]
	v_mfma_f32_16x16x32_bf16 v[104:107], v[166:169], v[200:203], v[104:107]
	v_mfma_f32_16x16x32_bf16 v[92:95], v[144:147], v[210:213], v[92:95]
	v_mfma_f32_16x16x32_bf16 v[88:91], v[166:169], v[210:213], v[88:91]
	v_mfma_f32_16x16x32_bf16 v[76:79], v[144:147], v[218:221], v[76:79]
	v_mfma_f32_16x16x32_bf16 v[72:75], v[166:169], v[218:221], v[72:75]
	v_mfma_f32_16x16x32_bf16 v[124:127], v[162:165], v[196:199], v[124:127]
	v_mfma_f32_16x16x32_bf16 v[120:123], v[170:173], v[196:199], v[120:123]
	v_mfma_f32_16x16x32_bf16 v[108:111], v[162:165], v[204:207], v[108:111]
	v_mfma_f32_16x16x32_bf16 v[104:107], v[170:173], v[204:207], v[104:107]
	v_mfma_f32_16x16x32_bf16 v[92:95], v[162:165], v[214:217], v[92:95]
	v_mfma_f32_16x16x32_bf16 v[88:91], v[170:173], v[214:217], v[88:91]
	v_mfma_f32_16x16x32_bf16 v[76:79], v[162:165], v[222:225], v[76:79]
	v_mfma_f32_16x16x32_bf16 v[72:75], v[170:173], v[222:225], v[72:75]
	v_mfma_f32_16x16x32_bf16 v[116:119], v[174:177], v[192:195], v[116:119]
	v_mfma_f32_16x16x32_bf16 v[112:115], v[184:187], v[192:195], v[112:115]
	v_mfma_f32_16x16x32_bf16 v[100:103], v[174:177], v[200:203], v[100:103]
	v_mfma_f32_16x16x32_bf16 v[96:99], v[184:187], v[200:203], v[96:99]
	v_mfma_f32_16x16x32_bf16 v[84:87], v[174:177], v[210:213], v[84:87]
	v_mfma_f32_16x16x32_bf16 v[80:83], v[184:187], v[210:213], v[80:83]
	v_mfma_f32_16x16x32_bf16 v[68:71], v[174:177], v[218:221], v[68:71]
	v_mfma_f32_16x16x32_bf16 v[64:67], v[184:187], v[218:221], v[64:67]
	v_mfma_f32_16x16x32_bf16 v[116:119], v[180:183], v[196:199], v[116:119]
	v_mfma_f32_16x16x32_bf16 v[112:115], v[188:191], v[196:199], v[112:115]
	v_mfma_f32_16x16x32_bf16 v[100:103], v[180:183], v[204:207], v[100:103]
	v_mfma_f32_16x16x32_bf16 v[96:99], v[188:191], v[204:207], v[96:99]
	v_mfma_f32_16x16x32_bf16 v[84:87], v[180:183], v[214:217], v[84:87]
	v_mfma_f32_16x16x32_bf16 v[80:83], v[188:191], v[214:217], v[80:83]
	v_mfma_f32_16x16x32_bf16 v[68:71], v[180:183], v[222:225], v[68:71]
	v_mfma_f32_16x16x32_bf16 v[64:67], v[188:191], v[222:225], v[64:67]
	s_setprio 0
	s_barrier
	s_add_i32 s24, s48, s26
	v_lshl_add_u64 v[226:227], v[226:227], 0, s[14:15]
	s_mov_b32 m0, s24
	ds_read_b128 v[192:195], v160 offset:49152
	ds_read_b128 v[196:199], v160 offset:50176
	ds_read_b128 v[200:203], v160 offset:51200
	ds_read_b128 v[204:207], v160 offset:52224
	ds_read_b128 v[210:213], v160 offset:53248
	ds_read_b128 v[214:217], v160 offset:54272
	ds_read_b128 v[218:221], v160 offset:55296
	ds_read_b128 v[222:225], v160 offset:56320
	global_load_lds_dwordx4 v[226:227], off
	s_add_i32 m0, s24, 0x2000
	s_add_u32 s22, s22, 0x160080
	v_lshl_add_u64 v[226:227], v[228:229], 0, s[14:15]
	s_addc_u32 s23, s23, 0
	s_add_i32 s24, s49, s26
	global_load_lds_dwordx4 v[226:227], off
	v_lshl_add_u64 v[226:227], s[22:23], 0, v[132:133]
	s_mov_b32 m0, s24
	s_nop 0
	global_load_lds_dwordx4 v[226:227], off
	v_lshl_add_u64 v[226:227], s[22:23], 0, v[136:137]
	s_add_i32 m0, s24, 0x2000
	s_nop 0
	global_load_lds_dwordx4 v[226:227], off
	v_lshl_add_u64 v[226:227], v[230:231], 0, s[14:15]
	s_mov_b32 m0, s2
	s_nop 0
	global_load_lds_dwordx4 v[226:227], off
	v_lshl_add_u64 v[226:227], v[232:233], 0, s[14:15]
	s_mov_b32 m0, s37
	s_nop 0
	global_load_lds_dwordx4 v[226:227], off
	s_waitcnt vmcnt(8)
	s_waitcnt lgkmcnt(0)
	s_barrier
	s_setprio 1
	v_mfma_f32_16x16x32_bf16 v[60:63], v[144:147], v[192:195], v[60:63]
	v_mfma_f32_16x16x32_bf16 v[56:59], v[166:169], v[192:195], v[56:59]
	v_mfma_f32_16x16x32_bf16 v[44:47], v[144:147], v[200:203], v[44:47]
	v_mfma_f32_16x16x32_bf16 v[40:43], v[166:169], v[200:203], v[40:43]
	v_mfma_f32_16x16x32_bf16 v[28:31], v[144:147], v[210:213], v[28:31]
	v_mfma_f32_16x16x32_bf16 v[24:27], v[166:169], v[210:213], v[24:27]
	v_mfma_f32_16x16x32_bf16 v[12:15], v[144:147], v[218:221], v[12:15]
	v_mfma_f32_16x16x32_bf16 v[8:11], v[166:169], v[218:221], v[8:11]
	v_mfma_f32_16x16x32_bf16 v[60:63], v[162:165], v[196:199], v[60:63]
	v_mfma_f32_16x16x32_bf16 v[56:59], v[170:173], v[196:199], v[56:59]
	v_mfma_f32_16x16x32_bf16 v[44:47], v[162:165], v[204:207], v[44:47]
	v_mfma_f32_16x16x32_bf16 v[40:43], v[170:173], v[204:207], v[40:43]
	v_mfma_f32_16x16x32_bf16 v[28:31], v[162:165], v[214:217], v[28:31]
	v_mfma_f32_16x16x32_bf16 v[24:27], v[170:173], v[214:217], v[24:27]
	v_mfma_f32_16x16x32_bf16 v[12:15], v[162:165], v[222:225], v[12:15]
	v_mfma_f32_16x16x32_bf16 v[8:11], v[170:173], v[222:225], v[8:11]
	v_mfma_f32_16x16x32_bf16 v[52:55], v[174:177], v[192:195], v[52:55]
	v_mfma_f32_16x16x32_bf16 v[48:51], v[184:187], v[192:195], v[48:51]
	v_mfma_f32_16x16x32_bf16 v[36:39], v[174:177], v[200:203], v[36:39]
	v_mfma_f32_16x16x32_bf16 v[32:35], v[184:187], v[200:203], v[32:35]
	v_mfma_f32_16x16x32_bf16 v[20:23], v[174:177], v[210:213], v[20:23]
	v_mfma_f32_16x16x32_bf16 v[16:19], v[184:187], v[210:213], v[16:19]
	v_mfma_f32_16x16x32_bf16 v[4:7], v[174:177], v[218:221], v[4:7]
	v_mfma_f32_16x16x32_bf16 v[0:3], v[184:187], v[218:221], v[0:3]
	v_mfma_f32_16x16x32_bf16 v[52:55], v[180:183], v[196:199], v[52:55]
	v_mfma_f32_16x16x32_bf16 v[48:51], v[188:191], v[196:199], v[48:51]
	v_mfma_f32_16x16x32_bf16 v[36:39], v[180:183], v[204:207], v[36:39]
	v_mfma_f32_16x16x32_bf16 v[32:35], v[188:191], v[204:207], v[32:35]
	v_mfma_f32_16x16x32_bf16 v[20:23], v[180:183], v[214:217], v[20:23]
	v_mfma_f32_16x16x32_bf16 v[16:19], v[188:191], v[214:217], v[16:19]
	v_mfma_f32_16x16x32_bf16 v[4:7], v[180:183], v[222:225], v[4:7]
	v_mfma_f32_16x16x32_bf16 v[0:3], v[188:191], v[222:225], v[0:3]
	s_setprio 0
	s_barrier
	s_add_i32 s47, s47, 2
	s_add_u32 s20, s20, 0x100
	s_addc_u32 s21, s21, 0
	s_add_u32 s45, s45, 0x100
	s_addc_u32 s46, s46, 0
	s_cmpk_gt_u32 s47, 0x55
	s_cbranch_scc0 .LBB0_1461
	s_and_b64 vcc, exec, s[16:17]
	s_cbranch_vccz .LBB0_1464
	s_barrier

.LBB0_1482:
	ds_read_b128 v[152:155], v129
	ds_read_b128 v[156:159], v129 offset:1024
	ds_read_b128 v[160:163], v129 offset:2048
	ds_read_b128 v[164:167], v129 offset:3072
	ds_read_b128 v[168:171], v145
	ds_read_b128 v[172:175], v145 offset:1024
	ds_read_b128 v[180:183], v145 offset:2048
	ds_read_b128 v[184:187], v145 offset:3072
	s_add_u32 s26, s24, 0xffea0080
	s_addc_u32 s27, s25, -1
	s_cmp_eq_u32 s71, 18
	s_cselect_b32 s29, s19, s27
	s_cselect_b32 s28, s18, s26
	s_cselect_b32 s27, s21, s70
	s_cselect_b32 s26, s20, s23
	v_lshl_add_u64 v[176:177], s[24:25], 0, v[140:141]
	s_add_i32 m0, s11, 0xc000
	ds_read_b128 v[188:191], v146
	ds_read_b128 v[192:195], v146 offset:1024
	ds_read_b128 v[196:199], v146 offset:2048
	ds_read_b128 v[200:203], v146 offset:3072
	ds_read_b128 v[204:207], v146 offset:4096
	ds_read_b128 v[208:211], v146 offset:5120
	ds_read_b128 v[212:215], v146 offset:6144
	ds_read_b128 v[216:219], v146 offset:7168
	global_load_lds_dwordx4 v[176:177], off
	v_lshl_add_u64 v[176:177], s[24:25], 0, v[142:143]
	s_add_i32 m0, s11, 0xe000
	s_nop 0
	global_load_lds_dwordx4 v[176:177], off
	s_waitcnt vmcnt(8)
	s_waitcnt lgkmcnt(0)
	s_barrier
	s_setprio 1
	v_mfma_f32_16x16x32_bf16 v[124:127], v[152:155], v[188:191], v[124:127]
	v_mfma_f32_16x16x32_bf16 v[120:123], v[160:163], v[188:191], v[120:123]
	v_mfma_f32_16x16x32_bf16 v[116:119], v[152:155], v[196:199], v[116:119]
	v_mfma_f32_16x16x32_bf16 v[112:115], v[160:163], v[196:199], v[112:115]
	v_mfma_f32_16x16x32_bf16 v[108:111], v[152:155], v[204:207], v[108:111]
	v_mfma_f32_16x16x32_bf16 v[104:107], v[160:163], v[204:207], v[104:107]
	v_mfma_f32_16x16x32_bf16 v[100:103], v[152:155], v[212:215], v[100:103]
	v_mfma_f32_16x16x32_bf16 v[96:99], v[160:163], v[212:215], v[96:99]
	v_mfma_f32_16x16x32_bf16 v[124:127], v[156:159], v[192:195], v[124:127]
	v_mfma_f32_16x16x32_bf16 v[120:123], v[164:167], v[192:195], v[120:123]
	v_mfma_f32_16x16x32_bf16 v[116:119], v[156:159], v[200:203], v[116:119]
	v_mfma_f32_16x16x32_bf16 v[112:115], v[164:167], v[200:203], v[112:115]
	v_mfma_f32_16x16x32_bf16 v[108:111], v[156:159], v[208:211], v[108:111]
	v_mfma_f32_16x16x32_bf16 v[104:107], v[164:167], v[208:211], v[104:107]
	v_mfma_f32_16x16x32_bf16 v[100:103], v[156:159], v[216:219], v[100:103]
	v_mfma_f32_16x16x32_bf16 v[96:99], v[164:167], v[216:219], v[96:99]
	v_mfma_f32_16x16x32_bf16 v[92:95], v[168:171], v[188:191], v[92:95]
	v_mfma_f32_16x16x32_bf16 v[88:91], v[180:183], v[188:191], v[88:91]
	v_mfma_f32_16x16x32_bf16 v[84:87], v[168:171], v[196:199], v[84:87]
	v_mfma_f32_16x16x32_bf16 v[80:83], v[180:183], v[196:199], v[80:83]
	v_mfma_f32_16x16x32_bf16 v[76:79], v[168:171], v[204:207], v[76:79]
	v_mfma_f32_16x16x32_bf16 v[72:75], v[180:183], v[204:207], v[72:75]
	v_mfma_f32_16x16x32_bf16 v[68:71], v[168:171], v[212:215], v[68:71]
	v_mfma_f32_16x16x32_bf16 v[64:67], v[180:183], v[212:215], v[64:67]
	v_mfma_f32_16x16x32_bf16 v[92:95], v[172:175], v[192:195], v[92:95]
	v_mfma_f32_16x16x32_bf16 v[88:91], v[184:187], v[192:195], v[88:91]
	v_mfma_f32_16x16x32_bf16 v[84:87], v[172:175], v[200:203], v[84:87]
	v_mfma_f32_16x16x32_bf16 v[80:83], v[184:187], v[200:203], v[80:83]
	v_mfma_f32_16x16x32_bf16 v[76:79], v[172:175], v[208:211], v[76:79]
	v_mfma_f32_16x16x32_bf16 v[72:75], v[184:187], v[208:211], v[72:75]
	v_mfma_f32_16x16x32_bf16 v[68:71], v[172:175], v[216:219], v[68:71]
	v_mfma_f32_16x16x32_bf16 v[64:67], v[184:187], v[216:219], v[64:67]
	s_setprio 0
	s_barrier
	s_add_i32 s72, s50, s3
	v_lshl_add_u64 v[176:177], s[26:27], 0, v[132:133]
	s_mov_b32 m0, s72
	ds_read_b128 v[188:191], v146 offset:16384
	ds_read_b128 v[192:195], v146 offset:17408
	ds_read_b128 v[196:199], v146 offset:18432
	ds_read_b128 v[200:203], v146 offset:19456
	ds_read_b128 v[204:207], v146 offset:20480
	ds_read_b128 v[208:211], v146 offset:21504
	ds_read_b128 v[212:215], v146 offset:22528
	ds_read_b128 v[216:219], v146 offset:23552
	global_load_lds_dwordx4 v[176:177], off
	s_add_i32 m0, s72, 0x2000
	s_add_u32 s72, s26, 0x160000
	v_lshl_add_u64 v[220:221], s[26:27], 0, v[136:137]
	s_addc_u32 s73, s27, 0
	s_add_i32 s74, s51, s3
	global_load_lds_dwordx4 v[220:221], off
	v_lshl_add_u64 v[222:223], s[72:73], 0, v[132:133]
	s_mov_b32 m0, s74
	v_lshl_add_u64 v[224:225], s[28:29], 0, v[134:135]
	global_load_lds_dwordx4 v[222:223], off
	v_lshl_add_u64 v[222:223], s[72:73], 0, v[136:137]
	s_add_i32 m0, s74, 0x2000
	s_nop 0
	global_load_lds_dwordx4 v[222:223], off
	v_lshl_add_u64 v[222:223], s[28:29], 0, v[130:131]
	s_mov_b32 m0, s11
	s_nop 0
	global_load_lds_dwordx4 v[222:223], off
	s_mov_b32 m0, s36
	s_nop 0
	global_load_lds_dwordx4 v[224:225], off
	s_waitcnt vmcnt(8)
	s_waitcnt lgkmcnt(0)
	s_barrier
	s_setprio 1
	v_mfma_f32_16x16x32_bf16 v[60:63], v[152:155], v[188:191], v[60:63]
	v_mfma_f32_16x16x32_bf16 v[56:59], v[160:163], v[188:191], v[56:59]
	v_mfma_f32_16x16x32_bf16 v[52:55], v[152:155], v[196:199], v[52:55]
	v_mfma_f32_16x16x32_bf16 v[48:51], v[160:163], v[196:199], v[48:51]
	v_mfma_f32_16x16x32_bf16 v[44:47], v[152:155], v[204:207], v[44:47]
	v_mfma_f32_16x16x32_bf16 v[40:43], v[160:163], v[204:207], v[40:43]
	v_mfma_f32_16x16x32_bf16 v[36:39], v[152:155], v[212:215], v[36:39]
	v_mfma_f32_16x16x32_bf16 v[32:35], v[160:163], v[212:215], v[32:35]
	v_mfma_f32_16x16x32_bf16 v[60:63], v[156:159], v[192:195], v[60:63]
	v_mfma_f32_16x16x32_bf16 v[56:59], v[164:167], v[192:195], v[56:59]
	v_mfma_f32_16x16x32_bf16 v[52:55], v[156:159], v[200:203], v[52:55]
	v_mfma_f32_16x16x32_bf16 v[48:51], v[164:167], v[200:203], v[48:51]
	v_mfma_f32_16x16x32_bf16 v[44:47], v[156:159], v[208:211], v[44:47]
	v_mfma_f32_16x16x32_bf16 v[40:43], v[164:167], v[208:211], v[40:43]
	v_mfma_f32_16x16x32_bf16 v[36:39], v[156:159], v[216:219], v[36:39]
	v_mfma_f32_16x16x32_bf16 v[32:35], v[164:167], v[216:219], v[32:35]
	v_mfma_f32_16x16x32_bf16 v[28:31], v[168:171], v[188:191], v[28:31]
	v_mfma_f32_16x16x32_bf16 v[24:27], v[180:183], v[188:191], v[24:27]
	v_mfma_f32_16x16x32_bf16 v[20:23], v[168:171], v[196:199], v[20:23]
	v_mfma_f32_16x16x32_bf16 v[16:19], v[180:183], v[196:199], v[16:19]
	v_mfma_f32_16x16x32_bf16 v[12:15], v[168:171], v[204:207], v[12:15]
	v_mfma_f32_16x16x32_bf16 v[8:11], v[180:183], v[204:207], v[8:11]
	v_mfma_f32_16x16x32_bf16 v[4:7], v[168:171], v[212:215], v[4:7]
	v_mfma_f32_16x16x32_bf16 v[0:3], v[180:183], v[212:215], v[0:3]
	v_mfma_f32_16x16x32_bf16 v[28:31], v[172:175], v[192:195], v[28:31]
	v_mfma_f32_16x16x32_bf16 v[24:27], v[184:187], v[192:195], v[24:27]
	v_mfma_f32_16x16x32_bf16 v[20:23], v[172:175], v[200:203], v[20:23]
	v_mfma_f32_16x16x32_bf16 v[16:19], v[184:187], v[200:203], v[16:19]
	v_mfma_f32_16x16x32_bf16 v[12:15], v[172:175], v[208:211], v[12:15]
	v_mfma_f32_16x16x32_bf16 v[8:11], v[184:187], v[208:211], v[8:11]
	v_mfma_f32_16x16x32_bf16 v[4:7], v[172:175], v[216:219], v[4:7]
	v_mfma_f32_16x16x32_bf16 v[0:3], v[184:187], v[216:219], v[0:3]
	s_setprio 0
	s_barrier
	s_add_i32 s72, 0, 0x18000
	v_add_u32_e32 v147, s72, v144
	s_add_i32 s73, 0, 0x1c000
	ds_read_b128 v[152:155], v147
	ds_read_b128 v[156:159], v147 offset:1024
	ds_read_b128 v[160:163], v147 offset:2048
	ds_read_b128 v[164:167], v147 offset:3072
	v_add_u32_e32 v147, s73, v144
	ds_read_b128 v[168:171], v147
	ds_read_b128 v[172:175], v147 offset:1024
	ds_read_b128 v[180:183], v147 offset:2048
	ds_read_b128 v[184:187], v147 offset:3072
	s_add_u32 s28, s28, 0x160000
	s_addc_u32 s29, s29, 0
	s_mov_b32 m0, s37
	v_lshl_add_u64 v[226:227], s[28:29], 0, v[130:131]
	ds_read_b128 v[188:191], v146 offset:32768
	ds_read_b128 v[192:195], v146 offset:33792
	ds_read_b128 v[196:199], v146 offset:34816
	ds_read_b128 v[200:203], v146 offset:35840
	ds_read_b128 v[204:207], v146 offset:36864
	ds_read_b128 v[208:211], v146 offset:37888
	ds_read_b128 v[212:215], v146 offset:38912
	ds_read_b128 v[216:219], v146 offset:39936
	global_load_lds_dwordx4 v[226:227], off
	v_lshl_add_u64 v[226:227], s[28:29], 0, v[134:135]
	s_mov_b32 m0, s38
	s_nop 0
	global_load_lds_dwordx4 v[226:227], off
	s_waitcnt vmcnt(8)
	s_waitcnt lgkmcnt(0)
	s_barrier
	s_setprio 1
	v_mfma_f32_16x16x32_bf16 v[124:127], v[152:155], v[188:191], v[124:127]
	v_mfma_f32_16x16x32_bf16 v[120:123], v[160:163], v[188:191], v[120:123]
	v_mfma_f32_16x16x32_bf16 v[116:119], v[152:155], v[196:199], v[116:119]
	v_mfma_f32_16x16x32_bf16 v[112:115], v[160:163], v[196:199], v[112:115]
	v_mfma_f32_16x16x32_bf16 v[108:111], v[152:155], v[204:207], v[108:111]
	v_mfma_f32_16x16x32_bf16 v[104:107], v[160:163], v[204:207], v[104:107]
	v_mfma_f32_16x16x32_bf16 v[100:103], v[152:155], v[212:215], v[100:103]
	v_mfma_f32_16x16x32_bf16 v[96:99], v[160:163], v[212:215], v[96:99]
	v_mfma_f32_16x16x32_bf16 v[124:127], v[156:159], v[192:195], v[124:127]
	v_mfma_f32_16x16x32_bf16 v[120:123], v[164:167], v[192:195], v[120:123]
	v_mfma_f32_16x16x32_bf16 v[116:119], v[156:159], v[200:203], v[116:119]
	v_mfma_f32_16x16x32_bf16 v[112:115], v[164:167], v[200:203], v[112:115]
	v_mfma_f32_16x16x32_bf16 v[108:111], v[156:159], v[208:211], v[108:111]
	v_mfma_f32_16x16x32_bf16 v[104:107], v[164:167], v[208:211], v[104:107]
	v_mfma_f32_16x16x32_bf16 v[100:103], v[156:159], v[216:219], v[100:103]
	v_mfma_f32_16x16x32_bf16 v[96:99], v[164:167], v[216:219], v[96:99]
	v_mfma_f32_16x16x32_bf16 v[92:95], v[168:171], v[188:191], v[92:95]
	v_mfma_f32_16x16x32_bf16 v[88:91], v[180:183], v[188:191], v[88:91]
	v_mfma_f32_16x16x32_bf16 v[84:87], v[168:171], v[196:199], v[84:87]
	v_mfma_f32_16x16x32_bf16 v[80:83], v[180:183], v[196:199], v[80:83]
	v_mfma_f32_16x16x32_bf16 v[76:79], v[168:171], v[204:207], v[76:79]
	v_mfma_f32_16x16x32_bf16 v[72:75], v[180:183], v[204:207], v[72:75]
	v_mfma_f32_16x16x32_bf16 v[68:71], v[168:171], v[212:215], v[68:71]
	v_mfma_f32_16x16x32_bf16 v[64:67], v[180:183], v[212:215], v[64:67]
	v_mfma_f32_16x16x32_bf16 v[92:95], v[172:175], v[192:195], v[92:95]
	v_mfma_f32_16x16x32_bf16 v[88:91], v[184:187], v[192:195], v[88:91]
	v_mfma_f32_16x16x32_bf16 v[84:87], v[172:175], v[200:203], v[84:87]
	v_mfma_f32_16x16x32_bf16 v[80:83], v[184:187], v[200:203], v[80:83]
	v_mfma_f32_16x16x32_bf16 v[76:79], v[172:175], v[208:211], v[76:79]
	v_mfma_f32_16x16x32_bf16 v[72:75], v[184:187], v[208:211], v[72:75]
	v_mfma_f32_16x16x32_bf16 v[68:71], v[172:175], v[216:219], v[68:71]
	v_mfma_f32_16x16x32_bf16 v[64:67], v[184:187], v[216:219], v[64:67]
	s_setprio 0
	s_barrier
	s_add_i32 s28, s72, s3
	v_lshl_add_u64 v[176:177], v[176:177], 0, s[14:15]
	s_mov_b32 m0, s28
	ds_read_b128 v[188:191], v146 offset:49152
	ds_read_b128 v[192:195], v146 offset:50176
	ds_read_b128 v[196:199], v146 offset:51200
	ds_read_b128 v[200:203], v146 offset:52224
	ds_read_b128 v[204:207], v146 offset:53248
	ds_read_b128 v[208:211], v146 offset:54272
	ds_read_b128 v[212:215], v146 offset:55296
	ds_read_b128 v[216:219], v146 offset:56320
	global_load_lds_dwordx4 v[176:177], off
	s_add_i32 m0, s28, 0x2000
	s_add_u32 s26, s26, 0x160080
	v_lshl_add_u64 v[176:177], v[220:221], 0, s[14:15]
	s_addc_u32 s27, s27, 0
	s_add_i32 s28, s73, s3
	global_load_lds_dwordx4 v[176:177], off
	v_lshl_add_u64 v[176:177], s[26:27], 0, v[132:133]
	s_mov_b32 m0, s28
	s_nop 0
	global_load_lds_dwordx4 v[176:177], off
	v_lshl_add_u64 v[176:177], s[26:27], 0, v[136:137]
	s_add_i32 m0, s28, 0x2000
	s_nop 0
	global_load_lds_dwordx4 v[176:177], off
	v_lshl_add_u64 v[176:177], v[222:223], 0, s[14:15]
	s_mov_b32 m0, s44
	s_nop 0
	global_load_lds_dwordx4 v[176:177], off
	v_lshl_add_u64 v[176:177], v[224:225], 0, s[14:15]
	s_mov_b32 m0, s45
	s_nop 0
	global_load_lds_dwordx4 v[176:177], off
	s_waitcnt vmcnt(8)
	s_waitcnt lgkmcnt(0)
	s_barrier
	s_setprio 1
	v_mfma_f32_16x16x32_bf16 v[60:63], v[152:155], v[188:191], v[60:63]
	v_mfma_f32_16x16x32_bf16 v[56:59], v[160:163], v[188:191], v[56:59]
	v_mfma_f32_16x16x32_bf16 v[52:55], v[152:155], v[196:199], v[52:55]
	v_mfma_f32_16x16x32_bf16 v[48:51], v[160:163], v[196:199], v[48:51]
	v_mfma_f32_16x16x32_bf16 v[44:47], v[152:155], v[204:207], v[44:47]
	v_mfma_f32_16x16x32_bf16 v[40:43], v[160:163], v[204:207], v[40:43]
	v_mfma_f32_16x16x32_bf16 v[36:39], v[152:155], v[212:215], v[36:39]
	v_mfma_f32_16x16x32_bf16 v[32:35], v[160:163], v[212:215], v[32:35]
	v_mfma_f32_16x16x32_bf16 v[60:63], v[156:159], v[192:195], v[60:63]
	v_mfma_f32_16x16x32_bf16 v[56:59], v[164:167], v[192:195], v[56:59]
	v_mfma_f32_16x16x32_bf16 v[52:55], v[156:159], v[200:203], v[52:55]
	v_mfma_f32_16x16x32_bf16 v[48:51], v[164:167], v[200:203], v[48:51]
	v_mfma_f32_16x16x32_bf16 v[44:47], v[156:159], v[208:211], v[44:47]
	v_mfma_f32_16x16x32_bf16 v[40:43], v[164:167], v[208:211], v[40:43]
	v_mfma_f32_16x16x32_bf16 v[36:39], v[156:159], v[216:219], v[36:39]
	v_mfma_f32_16x16x32_bf16 v[32:35], v[164:167], v[216:219], v[32:35]
	v_mfma_f32_16x16x32_bf16 v[28:31], v[168:171], v[188:191], v[28:31]
	v_mfma_f32_16x16x32_bf16 v[24:27], v[180:183], v[188:191], v[24:27]
	v_mfma_f32_16x16x32_bf16 v[20:23], v[168:171], v[196:199], v[20:23]
	v_mfma_f32_16x16x32_bf16 v[16:19], v[180:183], v[196:199], v[16:19]
	v_mfma_f32_16x16x32_bf16 v[12:15], v[168:171], v[204:207], v[12:15]
	v_mfma_f32_16x16x32_bf16 v[8:11], v[180:183], v[204:207], v[8:11]
	v_mfma_f32_16x16x32_bf16 v[4:7], v[168:171], v[212:215], v[4:7]
	v_mfma_f32_16x16x32_bf16 v[0:3], v[180:183], v[212:215], v[0:3]
	v_mfma_f32_16x16x32_bf16 v[28:31], v[172:175], v[192:195], v[28:31]
	v_mfma_f32_16x16x32_bf16 v[24:27], v[184:187], v[192:195], v[24:27]
	v_mfma_f32_16x16x32_bf16 v[20:23], v[172:175], v[200:203], v[20:23]
	v_mfma_f32_16x16x32_bf16 v[16:19], v[184:187], v[200:203], v[16:19]
	v_mfma_f32_16x16x32_bf16 v[12:15], v[172:175], v[208:211], v[12:15]
	v_mfma_f32_16x16x32_bf16 v[8:11], v[184:187], v[208:211], v[8:11]
	v_mfma_f32_16x16x32_bf16 v[4:7], v[172:175], v[216:219], v[4:7]
	v_mfma_f32_16x16x32_bf16 v[0:3], v[184:187], v[216:219], v[0:3]
	s_setprio 0
	s_barrier
	s_add_i32 s71, s71, 2
	s_add_u32 s24, s24, 0x100
	s_addc_u32 s25, s25, 0
	s_add_u32 s23, s23, 0x100
	s_addc_u32 s70, s70, 0
	s_cmp_gt_u32 s71, 19
	s_cbranch_scc0 .LBB0_1482
	s_and_b64 vcc, exec, s[16:17]
	s_cbranch_vccz .LBB0_1485
	s_barrier
